# v51 + nt hint on the read-once f32 base loads of the residual epilogues (P2,P8,P10)
# baseline (speedup 1.0000x reference)
.LBB0_232:
	v_lshl_add_u32 v64, s54, 8, v216
	v_lshl_or_b32 v140, s55, 8, v218
	v_ashrrev_i32_e32 v65, 31, v64
	v_readlane_b32 s60, v252, 0
	v_ashrrev_i32_e32 v141, 31, v140
	s_waitcnt lgkmcnt(0)
	v_lshlrev_b64 v[0:1], 13, v[64:65]
	v_readlane_b32 s61, v252, 1
	v_lshlrev_b64 v[16:17], 2, v[140:141]
	v_readlane_b32 s74, v252, 14
	v_lshl_add_u64 v[212:213], s[60:61], 0, v[0:1]
	v_lshl_add_u64 v[0:1], v[212:213], 0, v[16:17]
	v_readlane_b32 s75, v252, 15
	global_load_dwordx4 v[28:31], v[0:1], off nt
	global_load_dwordx4 v[40:43], v[0:1], off offset:64 nt
	global_load_dwordx4 v[52:55], v[0:1], off offset:512 nt
	v_lshl_add_u64 v[2:3], s[74:75], 0, v[16:17]
	global_load_dwordx4 v[12:15], v[2:3], off
	global_load_dwordx4 v[8:11], v[2:3], off offset:64
	global_load_dwordx4 v[4:7], v[2:3], off offset:512
	global_load_dwordx4 v[60:63], v[0:1], off offset:576 nt
	v_or_b32_e32 v66, 16, v64
	v_or_b32_e32 v214, 32, v64
	v_ashrrev_i32_e32 v67, 31, v66
	v_ashrrev_i32_e32 v215, 31, v214
	v_lshlrev_b64 v[18:19], 13, v[66:67]
	v_lshlrev_b64 v[20:21], 13, v[214:215]
	v_lshl_add_u64 v[18:19], s[60:61], 0, v[18:19]
	v_lshl_add_u64 v[20:21], s[60:61], 0, v[20:21]
	global_load_dwordx4 v[0:3], v[2:3], off offset:576
	v_lshl_add_u64 v[18:19], v[18:19], 0, v[16:17]
	v_lshl_add_u64 v[16:17], v[20:21], 0, v[16:17]
	global_load_dwordx4 v[56:59], v[18:19], off nt
	global_load_dwordx4 v[48:51], v[18:19], off offset:64 nt
	global_load_dwordx4 v[36:39], v[18:19], off offset:512 nt
	global_load_dwordx4 v[24:27], v[18:19], off offset:576 nt
	global_load_dwordx4 v[44:47], v[16:17], off nt
	global_load_dwordx4 v[32:35], v[16:17], off offset:64 nt
	global_load_dwordx4 v[20:23], v[16:17], off offset:512 nt
	s_nop 0
	global_load_dwordx4 v[16:19], v[16:17], off offset:576 nt
	v_and_b32_e32 v225, 64, v223
	v_xor_b32_e32 v224, 16, v223
	v_add_u32_e32 v225, 64, v225
	v_xor_b32_e32 v226, 32, v223
	v_cmp_lt_i32_e32 vcc, v224, v225
	v_readlane_b32 s62, v252, 2
	v_readlane_b32 s63, v252, 3
	v_readlane_b32 s64, v252, 4
	v_readlane_b32 s65, v252, 5
	v_readlane_b32 s66, v252, 6
	v_readlane_b32 s67, v252, 7
	v_readlane_b32 s68, v252, 8
	v_readlane_b32 s69, v252, 9
	v_readlane_b32 s70, v252, 10
	v_readlane_b32 s71, v252, 11
	v_readlane_b32 s72, v252, 12
	v_readlane_b32 s73, v252, 13
	v_cndmask_b32_e32 v224, v223, v224, vcc
	v_cmp_lt_i32_e32 vcc, v226, v225
	v_readlane_b32 s60, v252, 16
	v_readlane_b32 s74, v252, 30
	v_cndmask_b32_e32 v228, v223, v226, vcc
	v_lshlrev_b64 v[226:227], 11, v[64:65]
	v_lshl_add_u64 v[226:227], v[226:227], 0, v[140:141]
	v_readlane_b32 s75, v252, 31
	v_lshlrev_b32_e32 v225, 2, v224
	v_lshlrev_b32_e32 v224, 2, v228
	v_lshl_add_u64 v[228:229], v[226:227], 2, s[74:75]
	v_lshlrev_b64 v[226:227], 1, v[226:227]
	v_lshl_add_u64 v[230:231], s[12:13], 0, v[226:227]
	v_or_b32_e32 v232, 32, v226
	v_mov_b32_e32 v233, v227
	v_lshl_add_u64 v[232:233], s[12:13], 0, v[232:233]
	v_readlane_b32 s61, v252, 17
	v_readlane_b32 s62, v252, 18
	v_readlane_b32 s63, v252, 19
	v_readlane_b32 s64, v252, 20
	v_readlane_b32 s65, v252, 21
	v_readlane_b32 s66, v252, 22
	v_readlane_b32 s67, v252, 23
	v_readlane_b32 s68, v252, 24
	v_readlane_b32 s69, v252, 25
	v_readlane_b32 s70, v252, 26
	v_readlane_b32 s71, v252, 27
	v_readlane_b32 s72, v252, 28
	v_readlane_b32 s73, v252, 29
	s_waitcnt vmcnt(0)
	v_pk_add_f32 v[30:31], v[200:201], v[30:31]
	v_pk_add_f32 v[28:29], v[202:203], v[28:29]
	v_pk_add_f32 v[42:43], v[204:205], v[42:43]
	v_pk_add_f32 v[40:41], v[206:207], v[40:41]
	v_pk_add_f32 v[54:55], v[210:211], v[54:55]
	v_pk_add_f32 v[52:53], v[208:209], v[52:53]
	v_mul_f32_e32 v234, v29, v29
	v_mul_f32_e32 v235, v31, v31
	v_pk_mul_f32 v[200:201], v[14:15], v[30:31]
	v_pk_mul_f32 v[202:203], v[12:13], v[28:29]
	v_mul_f32_e32 v236, v41, v41
	v_mul_f32_e32 v237, v43, v43
	global_store_dwordx4 v[228:229], v[28:31], off
	v_pk_mul_f32 v[204:205], v[10:11], v[42:43]
	v_pk_mul_f32 v[206:207], v[8:9], v[40:41]
	v_mul_f32_e32 v238, v53, v53
	v_mul_f32_e32 v239, v55, v55
	v_fmac_f32_e32 v234, v28, v28
	v_fmac_f32_e32 v235, v30, v30
	v_cvt_pk_bf16_f32 v28, v202, v203
	v_cvt_pk_bf16_f32 v29, v200, v201
	v_fmac_f32_e32 v236, v40, v40
	v_fmac_f32_e32 v237, v42, v42
	v_cvt_pk_bf16_f32 v30, v206, v207
	v_cvt_pk_bf16_f32 v31, v204, v205
	v_fmac_f32_e32 v238, v52, v52
	v_fmac_f32_e32 v239, v54, v54
	v_add_f32_e32 v200, v234, v235
	global_store_dwordx2 v[230:231], v[28:29], off
	global_store_dwordx4 v[228:229], v[40:43], off offset:64
	v_add_f32_e32 v28, v236, v237
	v_pk_mul_f32 v[208:209], v[6:7], v[54:55]
	v_pk_mul_f32 v[210:211], v[4:5], v[52:53]
	global_store_dwordx2 v[232:233], v[30:31], off
	global_store_dwordx4 v[228:229], v[52:55], off offset:512
	v_add_f32_e32 v29, v238, v239
	v_add_f32_e32 v28, v200, v28
	v_or_b32_e32 v30, 0x100, v226
	v_mov_b32_e32 v31, v227
	v_add_f32_e32 v40, v28, v29
	v_cvt_pk_bf16_f32 v28, v210, v211
	v_cvt_pk_bf16_f32 v29, v208, v209
	v_lshl_add_u64 v[30:31], s[12:13], 0, v[30:31]
	global_store_dwordx2 v[30:31], v[28:29], off
	v_pk_add_f32 v[30:31], v[198:199], v[62:63]
	v_pk_add_f32 v[28:29], v[196:197], v[60:61]
	v_mul_f32_e32 v42, v31, v31
	v_mul_f32_e32 v41, v29, v29
	v_fmac_f32_e32 v41, v28, v28
	v_fmac_f32_e32 v42, v30, v30
	v_add_f32_e32 v41, v41, v42
	v_add_f32_e32 v41, v40, v41
	ds_bpermute_b32 v42, v225, v41
	global_store_dwordx4 v[228:229], v[28:31], off offset:576
	v_or_b32_e32 v226, 0x120, v226
	s_nop 0
	v_pk_mul_f32 v[28:29], v[0:1], v[28:29]
	v_pk_mul_f32 v[30:31], v[2:3], v[30:31]
	v_cvt_pk_bf16_f32 v40, v28, v29
	s_waitcnt lgkmcnt(0)
	v_add_f32_e32 v28, v41, v42
	ds_bpermute_b32 v29, v224, v28
	v_cvt_pk_bf16_f32 v41, v30, v31
	v_lshl_add_u64 v[30:31], s[12:13], 0, v[226:227]
	global_store_dwordx2 v[30:31], v[40:41], off
	s_and_saveexec_b64 s[24:25], s[4:5]
	s_cbranch_execz .LBB0_234
	v_lshl_add_u64 v[30:31], v[64:65], 2, s[14:15]
	s_waitcnt lgkmcnt(0)
	v_add_f32_e32 v28, v28, v29
	global_atomic_add_f32 v[30:31], v28, off
.LBB0_234:
	s_or_b64 exec, exec, s[24:25]
	v_or_b32_e32 v196, 48, v64
	v_ashrrev_i32_e32 v197, 31, v196
	v_readlane_b32 s60, v252, 0
	s_waitcnt lgkmcnt(0)
	v_lshlrev_b64 v[28:29], 13, v[196:197]
	v_readlane_b32 s61, v252, 1
	v_readlane_b32 s62, v252, 2
	v_readlane_b32 s63, v252, 3
	v_lshl_add_u64 v[28:29], s[60:61], 0, v[28:29]
	v_lshl_add_u64 v[28:29], v[140:141], 2, v[28:29]
	global_load_dwordx4 v[60:63], v[28:29], off nt
	global_load_dwordx4 v[52:55], v[28:29], off offset:64 nt
	global_load_dwordx4 v[40:43], v[28:29], off offset:512 nt
	s_nop 0
	global_load_dwordx4 v[28:31], v[28:29], off offset:576 nt
	v_readlane_b32 s64, v252, 4
	v_readlane_b32 s65, v252, 5
	v_readlane_b32 s66, v252, 6
	v_readlane_b32 s67, v252, 7
	v_readlane_b32 s68, v252, 8
	v_readlane_b32 s69, v252, 9
	v_readlane_b32 s70, v252, 10
	v_readlane_b32 s71, v252, 11
	v_readlane_b32 s72, v252, 12
	v_readlane_b32 s73, v252, 13
	v_readlane_b32 s74, v252, 14
	v_readlane_b32 s75, v252, 15
	v_lshlrev_b64 v[198:199], 11, v[66:67]
	v_readlane_b32 s60, v252, 16
	v_lshl_add_u64 v[198:199], v[198:199], 0, v[140:141]
	v_pk_add_f32 v[58:59], v[194:195], v[58:59]
	v_pk_add_f32 v[56:57], v[192:193], v[56:57]
	v_readlane_b32 s74, v252, 30
	v_readlane_b32 s75, v252, 31
	v_mul_f32_e32 v65, v57, v57
	v_mul_f32_e32 v194, v59, v59
	v_lshl_add_u64 v[192:193], v[198:199], 2, s[74:75]
	global_store_dwordx4 v[192:193], v[56:59], off
	v_fmac_f32_e32 v65, v56, v56
	v_fmac_f32_e32 v194, v58, v58
	v_pk_mul_f32 v[58:59], v[14:15], v[58:59]
	v_pk_mul_f32 v[56:57], v[12:13], v[56:57]
	v_add_f32_e32 v65, v65, v194
	v_cvt_pk_bf16_f32 v56, v56, v57
	v_cvt_pk_bf16_f32 v57, v58, v59
	v_lshlrev_b64 v[58:59], 1, v[198:199]
	v_lshl_add_u64 v[194:195], s[12:13], 0, v[58:59]
	v_pk_add_f32 v[50:51], v[190:191], v[50:51]
	v_pk_add_f32 v[48:49], v[188:189], v[48:49]
	global_store_dwordx2 v[194:195], v[56:57], off
	v_mul_f32_e32 v56, v49, v49
	v_mul_f32_e32 v57, v51, v51
	global_store_dwordx4 v[192:193], v[48:51], off offset:64
	v_fmac_f32_e32 v56, v48, v48
	v_fmac_f32_e32 v57, v50, v50
	v_pk_mul_f32 v[50:51], v[10:11], v[50:51]
	v_pk_mul_f32 v[48:49], v[8:9], v[48:49]
	v_pk_add_f32 v[38:39], v[186:187], v[38:39]
	v_cvt_pk_bf16_f32 v48, v48, v49
	v_cvt_pk_bf16_f32 v49, v50, v51
	v_or_b32_e32 v50, 32, v58
	v_mov_b32_e32 v51, v59
	v_lshl_add_u64 v[50:51], s[12:13], 0, v[50:51]
	v_pk_add_f32 v[36:37], v[184:185], v[36:37]
	global_store_dwordx2 v[50:51], v[48:49], off
	v_mul_f32_e32 v48, v37, v37
	v_mul_f32_e32 v49, v39, v39
	global_store_dwordx4 v[192:193], v[36:39], off offset:512
	v_fmac_f32_e32 v48, v36, v36
	v_fmac_f32_e32 v49, v38, v38
	v_pk_mul_f32 v[38:39], v[6:7], v[38:39]
	v_pk_mul_f32 v[36:37], v[4:5], v[36:37]
	v_pk_add_f32 v[26:27], v[182:183], v[26:27]
	v_cvt_pk_bf16_f32 v36, v36, v37
	v_cvt_pk_bf16_f32 v37, v38, v39
	v_or_b32_e32 v38, 0x100, v58
	v_mov_b32_e32 v39, v59
	v_lshl_add_u64 v[38:39], s[12:13], 0, v[38:39]
	v_pk_add_f32 v[24:25], v[180:181], v[24:25]
	v_add_f32_e32 v56, v56, v57
	global_store_dwordx2 v[38:39], v[36:37], off
	v_mul_f32_e32 v36, v25, v25
	v_mul_f32_e32 v37, v27, v27
	v_add_f32_e32 v56, v65, v56
	v_add_f32_e32 v48, v48, v49
	v_fmac_f32_e32 v36, v24, v24
	v_fmac_f32_e32 v37, v26, v26
	v_add_f32_e32 v48, v56, v48
	v_add_f32_e32 v36, v36, v37
	v_add_f32_e32 v37, v48, v36
	ds_bpermute_b32 v38, v225, v37
	global_store_dwordx4 v[192:193], v[24:27], off offset:576
	v_or_b32_e32 v58, 0x120, v58
	v_readlane_b32 s61, v252, 17
	v_pk_mul_f32 v[24:25], v[0:1], v[24:25]
	v_pk_mul_f32 v[26:27], v[2:3], v[26:27]
	v_cvt_pk_bf16_f32 v36, v24, v25
	s_waitcnt lgkmcnt(0)
	v_add_f32_e32 v24, v37, v38
	ds_bpermute_b32 v25, v224, v24
	v_cvt_pk_bf16_f32 v37, v26, v27
	v_lshl_add_u64 v[26:27], s[12:13], 0, v[58:59]
	v_readlane_b32 s62, v252, 18
	v_readlane_b32 s63, v252, 19
	v_readlane_b32 s64, v252, 20
	v_readlane_b32 s65, v252, 21
	v_readlane_b32 s66, v252, 22
	v_readlane_b32 s67, v252, 23
	v_readlane_b32 s68, v252, 24
	v_readlane_b32 s69, v252, 25
	v_readlane_b32 s70, v252, 26
	v_readlane_b32 s71, v252, 27
	v_readlane_b32 s72, v252, 28
	v_readlane_b32 s73, v252, 29
	global_store_dwordx2 v[26:27], v[36:37], off
	s_and_saveexec_b64 s[24:25], s[4:5]
	s_cbranch_execz .LBB0_236
	v_lshl_add_u64 v[26:27], v[66:67], 2, s[14:15]
	s_waitcnt lgkmcnt(0)
	v_add_f32_e32 v24, v24, v25
	global_atomic_add_f32 v[26:27], v24, off
.LBB0_236:
	s_or_b64 exec, exec, s[24:25]
	v_add_u32_e32 v180, 0x80, v64
	v_ashrrev_i32_e32 v181, 31, v180
	v_readlane_b32 s60, v252, 0
	s_waitcnt lgkmcnt(0)
	v_lshlrev_b64 v[24:25], 13, v[180:181]
	v_readlane_b32 s61, v252, 1
	v_readlane_b32 s62, v252, 2
	v_readlane_b32 s63, v252, 3
	v_lshl_add_u64 v[24:25], s[60:61], 0, v[24:25]
	v_lshl_add_u64 v[24:25], v[140:141], 2, v[24:25]
	global_load_dwordx4 v[64:67], v[24:25], off nt
	global_load_dwordx4 v[48:51], v[24:25], off offset:64 nt
	global_load_dwordx4 v[36:39], v[24:25], off offset:512 nt
	s_nop 0
	global_load_dwordx4 v[24:27], v[24:25], off offset:576 nt
	v_readlane_b32 s64, v252, 4
	v_readlane_b32 s65, v252, 5
	v_readlane_b32 s66, v252, 6
	v_readlane_b32 s67, v252, 7
	v_readlane_b32 s68, v252, 8
	v_readlane_b32 s69, v252, 9
	v_readlane_b32 s70, v252, 10
	v_readlane_b32 s71, v252, 11
	v_readlane_b32 s72, v252, 12
	v_readlane_b32 s73, v252, 13
	v_readlane_b32 s74, v252, 14
	v_readlane_b32 s75, v252, 15
	v_lshlrev_b64 v[56:57], 11, v[214:215]
	v_readlane_b32 s60, v252, 16
	v_lshl_add_u64 v[56:57], v[56:57], 0, v[140:141]
	v_pk_add_f32 v[46:47], v[178:179], v[46:47]
	v_pk_add_f32 v[44:45], v[176:177], v[44:45]
	v_readlane_b32 s74, v252, 30
	v_readlane_b32 s75, v252, 31
	v_mul_f32_e32 v176, v45, v45
	v_mul_f32_e32 v177, v47, v47
	v_lshl_add_u64 v[58:59], v[56:57], 2, s[74:75]
	global_store_dwordx4 v[58:59], v[44:47], off
	v_fmac_f32_e32 v176, v44, v44
	v_fmac_f32_e32 v177, v46, v46
	v_pk_mul_f32 v[46:47], v[14:15], v[46:47]
	v_pk_mul_f32 v[44:45], v[12:13], v[44:45]
	v_pk_add_f32 v[34:35], v[174:175], v[34:35]
	v_cvt_pk_bf16_f32 v44, v44, v45
	v_cvt_pk_bf16_f32 v45, v46, v47
	v_lshlrev_b64 v[46:47], 1, v[56:57]
	v_lshl_add_u64 v[56:57], s[12:13], 0, v[46:47]
	v_pk_add_f32 v[32:33], v[172:173], v[32:33]
	global_store_dwordx2 v[56:57], v[44:45], off
	v_mul_f32_e32 v44, v33, v33
	v_mul_f32_e32 v45, v35, v35
	global_store_dwordx4 v[58:59], v[32:35], off offset:64
	v_fmac_f32_e32 v44, v32, v32
	v_fmac_f32_e32 v45, v34, v34
	v_pk_mul_f32 v[34:35], v[10:11], v[34:35]
	v_pk_mul_f32 v[32:33], v[8:9], v[32:33]
	v_pk_add_f32 v[22:23], v[170:171], v[22:23]
	v_cvt_pk_bf16_f32 v32, v32, v33
	v_cvt_pk_bf16_f32 v33, v34, v35
	v_or_b32_e32 v34, 32, v46
	v_mov_b32_e32 v35, v47
	v_lshl_add_u64 v[34:35], s[12:13], 0, v[34:35]
	v_pk_add_f32 v[20:21], v[168:169], v[20:21]
	global_store_dwordx2 v[34:35], v[32:33], off
	v_mul_f32_e32 v32, v21, v21
	v_mul_f32_e32 v33, v23, v23
	global_store_dwordx4 v[58:59], v[20:23], off offset:512
	v_fmac_f32_e32 v32, v20, v20
	v_fmac_f32_e32 v33, v22, v22
	v_pk_mul_f32 v[22:23], v[6:7], v[22:23]
	v_pk_mul_f32 v[20:21], v[4:5], v[20:21]
	v_pk_add_f32 v[18:19], v[166:167], v[18:19]
	v_cvt_pk_bf16_f32 v20, v20, v21
	v_cvt_pk_bf16_f32 v21, v22, v23
	v_or_b32_e32 v22, 0x100, v46
	v_mov_b32_e32 v23, v47
	v_lshl_add_u64 v[22:23], s[12:13], 0, v[22:23]
	v_pk_add_f32 v[16:17], v[164:165], v[16:17]
	v_add_f32_e32 v176, v176, v177
	v_add_f32_e32 v44, v44, v45
	global_store_dwordx2 v[22:23], v[20:21], off
	v_mul_f32_e32 v20, v17, v17
	v_mul_f32_e32 v21, v19, v19
	v_add_f32_e32 v44, v176, v44
	v_add_f32_e32 v32, v32, v33
	v_fmac_f32_e32 v20, v16, v16
	v_fmac_f32_e32 v21, v18, v18
	v_add_f32_e32 v32, v44, v32
	v_add_f32_e32 v20, v20, v21
	v_add_f32_e32 v21, v32, v20
	ds_bpermute_b32 v22, v225, v21
	global_store_dwordx4 v[58:59], v[16:19], off offset:576
	v_or_b32_e32 v46, 0x120, v46
	v_readlane_b32 s61, v252, 17
	v_pk_mul_f32 v[16:17], v[0:1], v[16:17]
	v_pk_mul_f32 v[18:19], v[2:3], v[18:19]
	v_cvt_pk_bf16_f32 v20, v16, v17
	s_waitcnt lgkmcnt(0)
	v_add_f32_e32 v16, v21, v22
	ds_bpermute_b32 v17, v224, v16
	v_cvt_pk_bf16_f32 v21, v18, v19
	v_lshl_add_u64 v[18:19], s[12:13], 0, v[46:47]
	v_readlane_b32 s62, v252, 18
	v_readlane_b32 s63, v252, 19
	v_readlane_b32 s64, v252, 20
	v_readlane_b32 s65, v252, 21
	v_readlane_b32 s66, v252, 22
	v_readlane_b32 s67, v252, 23
	v_readlane_b32 s68, v252, 24
	v_readlane_b32 s69, v252, 25
	v_readlane_b32 s70, v252, 26
	v_readlane_b32 s71, v252, 27
	v_readlane_b32 s72, v252, 28
	v_readlane_b32 s73, v252, 29
	global_store_dwordx2 v[18:19], v[20:21], off
	s_and_saveexec_b64 s[24:25], s[4:5]
	s_cbranch_execz .LBB0_238
	v_lshl_add_u64 v[18:19], v[214:215], 2, s[14:15]
	s_waitcnt lgkmcnt(0)
	v_add_f32_e32 v16, v16, v17
	global_atomic_add_f32 v[18:19], v16, off
.LBB0_238:
	s_or_b64 exec, exec, s[24:25]
	s_waitcnt lgkmcnt(0)
	v_lshl_add_u64 v[16:17], v[140:141], 2, v[212:213]
	v_lshl_add_u64 v[18:19], v[16:17], 0, s[20:21]
	v_add_co_u32_e32 v16, vcc, 0x120000, v16
	v_lshlrev_b64 v[20:21], 11, v[196:197]
	s_nop 0
	v_addc_co_u32_e32 v17, vcc, 0, v17, vcc
	global_load_dwordx4 v[44:47], v[18:19], off offset:64 nt
	global_load_dwordx4 v[32:35], v[18:19], off offset:512 nt
	global_load_dwordx4 v[56:59], v[16:17], off nt
	s_nop 0
	global_load_dwordx4 v[16:19], v[18:19], off offset:576 nt
	v_lshl_add_u64 v[164:165], v[20:21], 0, v[140:141]
	s_waitcnt vmcnt(27)
	v_pk_add_f32 v[22:23], v[160:161], v[62:63]
	v_pk_add_f32 v[20:21], v[158:159], v[60:61]
	v_readlane_b32 s60, v252, 16
	v_readlane_b32 s74, v252, 30
	v_readlane_b32 s75, v252, 31
	v_mul_f32_e32 v62, v21, v21
	v_mul_f32_e32 v63, v23, v23
	v_lshl_add_u64 v[60:61], v[164:165], 2, s[74:75]
	v_fmac_f32_e32 v62, v20, v20
	v_fmac_f32_e32 v63, v22, v22
	global_store_dwordx4 v[60:61], v[20:23], off
	v_add_f32_e32 v158, v62, v63
	v_lshlrev_b64 v[62:63], 1, v[164:165]
	v_pk_mul_f32 v[22:23], v[14:15], v[22:23]
	v_pk_mul_f32 v[20:21], v[12:13], v[20:21]
	v_readlane_b32 s61, v252, 17
	v_cvt_pk_bf16_f32 v20, v20, v21
	v_cvt_pk_bf16_f32 v21, v22, v23
	v_lshl_add_u64 v[22:23], s[12:13], 0, v[62:63]
	global_store_dwordx2 v[22:23], v[20:21], off
	s_waitcnt vmcnt(28)
	v_pk_add_f32 v[22:23], v[156:157], v[54:55]
	v_pk_add_f32 v[20:21], v[154:155], v[52:53]
	v_mul_f32_e32 v53, v23, v23
	v_mul_f32_e32 v52, v21, v21
	global_store_dwordx4 v[60:61], v[20:23], off offset:64
	v_fmac_f32_e32 v52, v20, v20
	v_fmac_f32_e32 v53, v22, v22
	v_pk_mul_f32 v[22:23], v[10:11], v[22:23]
	v_pk_mul_f32 v[20:21], v[8:9], v[20:21]
	v_add_f32_e32 v52, v52, v53
	v_cvt_pk_bf16_f32 v20, v20, v21
	v_cvt_pk_bf16_f32 v21, v22, v23
	v_or_b32_e32 v22, 32, v62
	v_mov_b32_e32 v23, v63
	v_lshl_add_u64 v[22:23], s[12:13], 0, v[22:23]
	global_store_dwordx2 v[22:23], v[20:21], off
	s_waitcnt vmcnt(29)
	v_pk_add_f32 v[22:23], v[152:153], v[42:43]
	v_pk_add_f32 v[20:21], v[150:151], v[40:41]
	v_mul_f32_e32 v41, v23, v23
	v_mul_f32_e32 v40, v21, v21
	global_store_dwordx4 v[60:61], v[20:23], off offset:512
	v_fmac_f32_e32 v40, v20, v20
	v_fmac_f32_e32 v41, v22, v22
	v_pk_mul_f32 v[22:23], v[6:7], v[22:23]
	v_pk_mul_f32 v[20:21], v[4:5], v[20:21]
	v_add_f32_e32 v52, v158, v52
	v_cvt_pk_bf16_f32 v20, v20, v21
	v_cvt_pk_bf16_f32 v21, v22, v23
	v_or_b32_e32 v22, 0x100, v62
	v_mov_b32_e32 v23, v63
	v_lshl_add_u64 v[22:23], s[12:13], 0, v[22:23]
	global_store_dwordx2 v[22:23], v[20:21], off
	s_waitcnt vmcnt(30)
	v_pk_add_f32 v[22:23], v[148:149], v[30:31]
	v_pk_add_f32 v[20:21], v[146:147], v[28:29]
	v_mul_f32_e32 v29, v23, v23
	v_mul_f32_e32 v28, v21, v21
	v_add_f32_e32 v40, v40, v41
	v_fmac_f32_e32 v28, v20, v20
	v_fmac_f32_e32 v29, v22, v22
	v_add_f32_e32 v40, v52, v40
	v_add_f32_e32 v28, v28, v29
	v_add_f32_e32 v29, v40, v28
	ds_bpermute_b32 v30, v225, v29
	global_store_dwordx4 v[60:61], v[20:23], off offset:576
	v_or_b32_e32 v62, 0x120, v62
	v_readlane_b32 s62, v252, 18
	v_pk_mul_f32 v[20:21], v[0:1], v[20:21]
	v_pk_mul_f32 v[22:23], v[2:3], v[22:23]
	v_cvt_pk_bf16_f32 v28, v20, v21
	s_waitcnt lgkmcnt(0)
	v_add_f32_e32 v20, v29, v30
	ds_bpermute_b32 v21, v224, v20
	v_cvt_pk_bf16_f32 v29, v22, v23
	v_lshl_add_u64 v[22:23], s[12:13], 0, v[62:63]
	v_readlane_b32 s63, v252, 19
	v_readlane_b32 s64, v252, 20
	v_readlane_b32 s65, v252, 21
	v_readlane_b32 s66, v252, 22
	v_readlane_b32 s67, v252, 23
	v_readlane_b32 s68, v252, 24
	v_readlane_b32 s69, v252, 25
	v_readlane_b32 s70, v252, 26
	v_readlane_b32 s71, v252, 27
	v_readlane_b32 s72, v252, 28
	v_readlane_b32 s73, v252, 29
	global_store_dwordx2 v[22:23], v[28:29], off
	s_and_saveexec_b64 s[24:25], s[4:5]
	s_cbranch_execz .LBB0_240
	v_lshl_add_u64 v[22:23], v[196:197], 2, s[14:15]
	s_waitcnt lgkmcnt(0)
	v_add_f32_e32 v20, v20, v21
	global_atomic_add_f32 v[22:23], v20, off
.LBB0_240:
	s_or_b64 exec, exec, s[24:25]
	v_or_b32_e32 v146, 32, v180
	v_ashrrev_i32_e32 v147, 31, v146
	v_readlane_b32 s60, v252, 0
	s_waitcnt lgkmcnt(0)
	v_lshlrev_b64 v[20:21], 13, v[146:147]
	v_readlane_b32 s61, v252, 1
	v_readlane_b32 s62, v252, 2
	v_readlane_b32 s63, v252, 3
	v_lshl_add_u64 v[20:21], s[60:61], 0, v[20:21]
	v_lshl_add_u64 v[20:21], v[140:141], 2, v[20:21]
	global_load_dwordx4 v[52:55], v[20:21], off nt
	global_load_dwordx4 v[40:43], v[20:21], off offset:64 nt
	global_load_dwordx4 v[28:31], v[20:21], off offset:512 nt
	s_nop 0
	global_load_dwordx4 v[20:23], v[20:21], off offset:576 nt
	v_readlane_b32 s64, v252, 4
	v_readlane_b32 s65, v252, 5
	v_readlane_b32 s66, v252, 6
	v_readlane_b32 s67, v252, 7
	v_readlane_b32 s68, v252, 8
	v_readlane_b32 s69, v252, 9
	v_readlane_b32 s70, v252, 10
	v_readlane_b32 s71, v252, 11
	v_readlane_b32 s72, v252, 12
	v_readlane_b32 s73, v252, 13
	v_readlane_b32 s74, v252, 14
	v_readlane_b32 s75, v252, 15
	v_lshlrev_b64 v[60:61], 11, v[180:181]
	v_readlane_b32 s60, v252, 16
	v_lshl_add_u64 v[148:149], v[60:61], 0, v[140:141]
	s_waitcnt vmcnt(27)
	v_pk_add_f32 v[62:63], v[144:145], v[66:67]
	v_pk_add_f32 v[60:61], v[142:143], v[64:65]
	v_readlane_b32 s74, v252, 30
	v_readlane_b32 s75, v252, 31
	v_mul_f32_e32 v66, v61, v61
	v_mul_f32_e32 v67, v63, v63
	v_lshl_add_u64 v[64:65], v[148:149], 2, s[74:75]
	global_store_dwordx4 v[64:65], v[60:63], off
	v_fmac_f32_e32 v66, v60, v60
	v_fmac_f32_e32 v67, v62, v62
	v_pk_mul_f32 v[62:63], v[14:15], v[62:63]
	v_pk_mul_f32 v[60:61], v[12:13], v[60:61]
	v_add_f32_e32 v142, v66, v67
	v_cvt_pk_bf16_f32 v60, v60, v61
	v_cvt_pk_bf16_f32 v61, v62, v63
	v_lshlrev_b64 v[62:63], 1, v[148:149]
	v_lshl_add_u64 v[66:67], s[12:13], 0, v[62:63]
	s_waitcnt vmcnt(27)
	v_pk_add_f32 v[50:51], v[126:127], v[50:51]
	v_pk_add_f32 v[48:49], v[124:125], v[48:49]
	global_store_dwordx2 v[66:67], v[60:61], off
	v_mul_f32_e32 v60, v49, v49
	v_mul_f32_e32 v61, v51, v51
	global_store_dwordx4 v[64:65], v[48:51], off offset:64
	v_fmac_f32_e32 v60, v48, v48
	v_fmac_f32_e32 v61, v50, v50
	v_pk_mul_f32 v[50:51], v[10:11], v[50:51]
	v_pk_mul_f32 v[48:49], v[8:9], v[48:49]
	s_waitcnt vmcnt(28)
	v_pk_add_f32 v[38:39], v[122:123], v[38:39]
	v_cvt_pk_bf16_f32 v48, v48, v49
	v_cvt_pk_bf16_f32 v49, v50, v51
	v_or_b32_e32 v50, 32, v62
	v_mov_b32_e32 v51, v63
	v_lshl_add_u64 v[50:51], s[12:13], 0, v[50:51]
	v_pk_add_f32 v[36:37], v[120:121], v[36:37]
	global_store_dwordx2 v[50:51], v[48:49], off
	v_mul_f32_e32 v48, v37, v37
	v_mul_f32_e32 v49, v39, v39
	global_store_dwordx4 v[64:65], v[36:39], off offset:512
	v_fmac_f32_e32 v48, v36, v36
	v_fmac_f32_e32 v49, v38, v38
	v_pk_mul_f32 v[38:39], v[6:7], v[38:39]
	v_pk_mul_f32 v[36:37], v[4:5], v[36:37]
	s_waitcnt vmcnt(29)
	v_pk_add_f32 v[26:27], v[118:119], v[26:27]
	v_cvt_pk_bf16_f32 v36, v36, v37
	v_cvt_pk_bf16_f32 v37, v38, v39
	v_or_b32_e32 v38, 0x100, v62
	v_mov_b32_e32 v39, v63
	v_lshl_add_u64 v[38:39], s[12:13], 0, v[38:39]
	v_pk_add_f32 v[24:25], v[116:117], v[24:25]
	v_add_f32_e32 v60, v60, v61
	global_store_dwordx2 v[38:39], v[36:37], off
	v_mul_f32_e32 v36, v25, v25
	v_mul_f32_e32 v37, v27, v27
	v_add_f32_e32 v60, v142, v60
	v_add_f32_e32 v48, v48, v49
	v_fmac_f32_e32 v36, v24, v24
	v_fmac_f32_e32 v37, v26, v26
	v_add_f32_e32 v48, v60, v48
	v_add_f32_e32 v36, v36, v37
	v_add_f32_e32 v37, v48, v36
	ds_bpermute_b32 v38, v225, v37
	global_store_dwordx4 v[64:65], v[24:27], off offset:576
	v_or_b32_e32 v62, 0x120, v62
	v_readlane_b32 s61, v252, 17
	v_pk_mul_f32 v[24:25], v[0:1], v[24:25]
	v_pk_mul_f32 v[26:27], v[2:3], v[26:27]
	v_cvt_pk_bf16_f32 v36, v24, v25
	s_waitcnt lgkmcnt(0)
	v_add_f32_e32 v24, v37, v38
	ds_bpermute_b32 v25, v224, v24
	v_cvt_pk_bf16_f32 v37, v26, v27
	v_lshl_add_u64 v[26:27], s[12:13], 0, v[62:63]
	v_readlane_b32 s62, v252, 18
	v_readlane_b32 s63, v252, 19
	v_readlane_b32 s64, v252, 20
	v_readlane_b32 s65, v252, 21
	v_readlane_b32 s66, v252, 22
	v_readlane_b32 s67, v252, 23
	v_readlane_b32 s68, v252, 24
	v_readlane_b32 s69, v252, 25
	v_readlane_b32 s70, v252, 26
	v_readlane_b32 s71, v252, 27
	v_readlane_b32 s72, v252, 28
	v_readlane_b32 s73, v252, 29
	global_store_dwordx2 v[26:27], v[36:37], off
	s_and_saveexec_b64 s[24:25], s[4:5]
	s_cbranch_execz .LBB0_242
	v_lshl_add_u64 v[26:27], v[180:181], 2, s[14:15]
	s_waitcnt lgkmcnt(0)
	v_add_f32_e32 v24, v24, v25
	global_atomic_add_f32 v[26:27], v24, off
.LBB0_242:
	s_or_b64 exec, exec, s[24:25]
	v_or_b32_e32 v64, 48, v180
	v_ashrrev_i32_e32 v65, 31, v64
	v_readlane_b32 s60, v252, 0
	s_waitcnt lgkmcnt(0)
	v_lshlrev_b64 v[24:25], 13, v[64:65]
	v_readlane_b32 s61, v252, 1
	v_or_b32_e32 v66, 16, v180
	v_readlane_b32 s62, v252, 2
	v_lshl_add_u64 v[24:25], s[60:61], 0, v[24:25]
	v_lshl_add_u64 v[24:25], v[140:141], 2, v[24:25]
	global_load_dwordx4 v[60:63], v[24:25], off nt
	global_load_dwordx4 v[48:51], v[24:25], off offset:64 nt
	global_load_dwordx4 v[36:39], v[24:25], off offset:512 nt
	s_nop 0
	global_load_dwordx4 v[24:27], v[24:25], off offset:576 nt
	v_readlane_b32 s63, v252, 3
	v_readlane_b32 s64, v252, 4
	v_readlane_b32 s65, v252, 5
	v_readlane_b32 s66, v252, 6
	v_readlane_b32 s67, v252, 7
	v_readlane_b32 s68, v252, 8
	v_readlane_b32 s69, v252, 9
	v_readlane_b32 s70, v252, 10
	v_readlane_b32 s71, v252, 11
	v_readlane_b32 s72, v252, 12
	v_readlane_b32 s73, v252, 13
	v_readlane_b32 s74, v252, 14
	v_readlane_b32 s75, v252, 15
	v_ashrrev_i32_e32 v67, 31, v66
	v_lshlrev_b64 v[116:117], 11, v[66:67]
	v_readlane_b32 s60, v252, 16
	v_lshl_add_u64 v[116:117], v[116:117], 0, v[140:141]
	s_waitcnt vmcnt(25)
	v_pk_add_f32 v[58:59], v[114:115], v[58:59]
	v_pk_add_f32 v[56:57], v[112:113], v[56:57]
	v_readlane_b32 s74, v252, 30
	v_readlane_b32 s75, v252, 31
	v_mul_f32_e32 v114, v57, v57
	v_mul_f32_e32 v115, v59, v59
	v_lshl_add_u64 v[112:113], v[116:117], 2, s[74:75]
	global_store_dwordx4 v[112:113], v[56:59], off
	v_fmac_f32_e32 v114, v56, v56
	v_fmac_f32_e32 v115, v58, v58
	v_pk_mul_f32 v[58:59], v[14:15], v[58:59]
	v_pk_mul_f32 v[56:57], v[12:13], v[56:57]
	v_add_f32_e32 v118, v114, v115
	v_cvt_pk_bf16_f32 v56, v56, v57
	v_cvt_pk_bf16_f32 v57, v58, v59
	v_lshlrev_b64 v[58:59], 1, v[116:117]
	v_lshl_add_u64 v[114:115], s[12:13], 0, v[58:59]
	v_pk_add_f32 v[46:47], v[110:111], v[46:47]
	v_pk_add_f32 v[44:45], v[108:109], v[44:45]
	global_store_dwordx2 v[114:115], v[56:57], off
	v_mul_f32_e32 v56, v45, v45
	v_mul_f32_e32 v57, v47, v47
	global_store_dwordx4 v[112:113], v[44:47], off offset:64
	v_fmac_f32_e32 v56, v44, v44
	v_fmac_f32_e32 v57, v46, v46
	v_pk_mul_f32 v[46:47], v[10:11], v[46:47]
	v_pk_mul_f32 v[44:45], v[8:9], v[44:45]
	v_pk_add_f32 v[34:35], v[106:107], v[34:35]
	v_cvt_pk_bf16_f32 v44, v44, v45
	v_cvt_pk_bf16_f32 v45, v46, v47
	v_or_b32_e32 v46, 32, v58
	v_mov_b32_e32 v47, v59
	v_lshl_add_u64 v[46:47], s[12:13], 0, v[46:47]
	v_pk_add_f32 v[32:33], v[104:105], v[32:33]
	global_store_dwordx2 v[46:47], v[44:45], off
	v_mul_f32_e32 v44, v33, v33
	v_mul_f32_e32 v45, v35, v35
	global_store_dwordx4 v[112:113], v[32:35], off offset:512
	v_fmac_f32_e32 v44, v32, v32
	v_fmac_f32_e32 v45, v34, v34
	v_pk_mul_f32 v[34:35], v[6:7], v[34:35]
	v_pk_mul_f32 v[32:33], v[4:5], v[32:33]
	s_waitcnt vmcnt(29)
	v_pk_add_f32 v[18:19], v[102:103], v[18:19]
	v_cvt_pk_bf16_f32 v32, v32, v33
	v_cvt_pk_bf16_f32 v33, v34, v35
	v_or_b32_e32 v34, 0x100, v58
	v_mov_b32_e32 v35, v59
	v_lshl_add_u64 v[34:35], s[12:13], 0, v[34:35]
	v_pk_add_f32 v[16:17], v[100:101], v[16:17]
	v_add_f32_e32 v56, v56, v57
	global_store_dwordx2 v[34:35], v[32:33], off
	v_mul_f32_e32 v32, v17, v17
	v_mul_f32_e32 v33, v19, v19
	v_add_f32_e32 v56, v118, v56
	v_add_f32_e32 v44, v44, v45
	v_fmac_f32_e32 v32, v16, v16
	v_fmac_f32_e32 v33, v18, v18
	v_add_f32_e32 v44, v56, v44
	v_add_f32_e32 v32, v32, v33
	v_add_f32_e32 v33, v44, v32
	ds_bpermute_b32 v34, v225, v33
	global_store_dwordx4 v[112:113], v[16:19], off offset:576
	v_or_b32_e32 v58, 0x120, v58
	v_readlane_b32 s61, v252, 17
	v_pk_mul_f32 v[16:17], v[0:1], v[16:17]
	v_pk_mul_f32 v[18:19], v[2:3], v[18:19]
	v_cvt_pk_bf16_f32 v32, v16, v17
	s_waitcnt lgkmcnt(0)
	v_add_f32_e32 v16, v33, v34
	ds_bpermute_b32 v17, v224, v16
	v_cvt_pk_bf16_f32 v33, v18, v19
	v_lshl_add_u64 v[18:19], s[12:13], 0, v[58:59]
	v_readlane_b32 s62, v252, 18
	v_readlane_b32 s63, v252, 19
	v_readlane_b32 s64, v252, 20
	v_readlane_b32 s65, v252, 21
	v_readlane_b32 s66, v252, 22
	v_readlane_b32 s67, v252, 23
	v_readlane_b32 s68, v252, 24
	v_readlane_b32 s69, v252, 25
	v_readlane_b32 s70, v252, 26
	v_readlane_b32 s71, v252, 27
	v_readlane_b32 s72, v252, 28
	v_readlane_b32 s73, v252, 29
	global_store_dwordx2 v[18:19], v[32:33], off
	s_and_saveexec_b64 s[24:25], s[4:5]
	s_cbranch_execz .LBB0_244
	v_lshl_add_u64 v[18:19], v[66:67], 2, s[14:15]
	s_waitcnt lgkmcnt(0)
	v_add_f32_e32 v16, v16, v17
	global_atomic_add_f32 v[18:19], v16, off

.LBB0_852:
	v_lshl_add_u32 v200, s54, 8, v206
	v_readlane_b32 s60, v252, 16
	v_lshl_or_b32 v188, s55, 8, v208
	v_ashrrev_i32_e32 v201, 31, v200
	v_readlane_b32 s74, v252, 30
	v_readlane_b32 s75, v252, 31
	v_ashrrev_i32_e32 v189, 31, v188
	v_lshlrev_b64 v[112:113], 13, v[200:201]
	v_readlane_b32 s72, v252, 28
	v_readlane_b32 s73, v252, 29
	s_mov_b64 s[82:83], s[74:75]
	v_lshlrev_b64 v[144:145], 2, v[188:189]
	v_readlane_b32 s61, v252, 17
	v_readlane_b32 s62, v252, 18
	v_readlane_b32 s63, v252, 19
	v_readlane_b32 s64, v252, 20
	v_readlane_b32 s65, v252, 21
	v_readlane_b32 s66, v252, 22
	v_readlane_b32 s67, v252, 23
	v_readlane_b32 s68, v252, 24
	v_readlane_b32 s69, v252, 25
	v_readlane_b32 s70, v252, 26
	v_readlane_b32 s71, v252, 27
	v_lshl_add_u64 v[190:191], s[82:83], 0, v[112:113]
	s_mov_b64 s[80:81], s[72:73]
	v_lshl_add_u64 v[230:231], v[190:191], 0, v[144:145]
	v_readlane_b32 s60, v252, 32
	global_load_dwordx4 v[196:199], v[230:231], off nt
	global_load_dwordx4 v[216:219], v[230:231], off offset:64 nt
	global_load_dwordx4 v[222:225], v[230:231], off offset:512 nt
	v_readlane_b32 s74, v252, 46
	v_readlane_b32 s75, v252, 47
	v_or_b32_e32 v202, 16, v200
	v_or_b32_e32 v192, 32, v200
	v_lshl_add_u64 v[112:113], s[74:75], 0, v[144:145]
	global_load_dwordx4 v[128:131], v[112:113], off
	global_load_dwordx4 v[120:123], v[112:113], off offset:64
	global_load_dwordx4 v[116:119], v[112:113], off offset:512
	global_load_dwordx4 v[226:229], v[230:231], off offset:576 nt
	v_ashrrev_i32_e32 v203, 31, v202
	v_ashrrev_i32_e32 v193, 31, v192
	v_lshlrev_b64 v[146:147], 13, v[202:203]
	v_lshlrev_b64 v[148:149], 13, v[192:193]
	v_lshl_add_u64 v[146:147], s[82:83], 0, v[146:147]
	global_load_dwordx4 v[112:115], v[112:113], off offset:576
	v_lshl_add_u64 v[148:149], s[82:83], 0, v[148:149]
	v_lshl_add_u64 v[204:205], v[146:147], 0, v[144:145]
	v_lshl_add_u64 v[194:195], v[148:149], 0, v[144:145]
	global_load_dwordx4 v[172:175], v[204:205], off nt
	global_load_dwordx4 v[168:171], v[204:205], off offset:64 nt
	global_load_dwordx4 v[164:167], v[204:205], off offset:512 nt
	global_load_dwordx4 v[160:163], v[204:205], off offset:576 nt
	global_load_dwordx4 v[156:159], v[194:195], off nt
	global_load_dwordx4 v[152:155], v[194:195], off offset:64 nt
	global_load_dwordx4 v[148:151], v[194:195], off offset:512 nt
	global_load_dwordx4 v[144:147], v[194:195], off offset:576 nt
	v_and_b32_e32 v214, 64, v212
	v_xor_b32_e32 v213, 16, v212
	v_add_u32_e32 v214, 64, v214
	v_xor_b32_e32 v215, 32, v212
	v_cmp_lt_i32_e32 vcc, v213, v214
	v_lshlrev_b64 v[232:233], 11, v[200:201]
	v_lshl_add_u64 v[232:233], v[232:233], 0, v[188:189]
	v_cndmask_b32_e32 v213, v212, v213, vcc
	v_cmp_lt_i32_e32 vcc, v215, v214
	v_lshlrev_b32_e32 v214, 2, v213
	v_lshlrev_b64 v[232:233], 1, v[232:233]
	v_cndmask_b32_e32 v215, v212, v215, vcc
	v_lshlrev_b32_e32 v213, 2, v215
	v_lshl_add_u64 v[234:235], s[14:15], 0, v[232:233]
	v_or_b32_e32 v236, 32, v232
	v_mov_b32_e32 v237, v233
	v_lshl_add_u64 v[236:237], s[14:15], 0, v[236:237]
	v_readlane_b32 s61, v252, 33
	v_readlane_b32 s62, v252, 34
	v_readlane_b32 s63, v252, 35
	v_readlane_b32 s64, v252, 36
	v_readlane_b32 s65, v252, 37
	v_readlane_b32 s66, v252, 38
	v_readlane_b32 s67, v252, 39
	v_readlane_b32 s68, v252, 40
	v_readlane_b32 s69, v252, 41
	v_readlane_b32 s70, v252, 42
	v_readlane_b32 s71, v252, 43
	v_readlane_b32 s72, v252, 44
	v_readlane_b32 s73, v252, 45
	s_waitcnt vmcnt(0)
	v_pk_add_f32 v[138:139], v[138:139], v[198:199]
	v_pk_add_f32 v[136:137], v[136:137], v[196:197]
	v_pk_add_f32 v[142:143], v[142:143], v[218:219]
	v_pk_add_f32 v[140:141], v[140:141], v[216:217]
	v_pk_add_f32 v[134:135], v[134:135], v[224:225]
	v_pk_add_f32 v[132:133], v[132:133], v[222:223]
	v_mul_f32_e32 v215, v137, v137
	v_mul_f32_e32 v221, v139, v139
	v_pk_mul_f32 v[196:197], v[130:131], v[138:139]
	v_pk_mul_f32 v[198:199], v[128:129], v[136:137]
	v_mul_f32_e32 v238, v141, v141
	v_mul_f32_e32 v239, v143, v143
	global_store_dwordx4 v[230:231], v[136:139], off
	v_pk_mul_f32 v[216:217], v[122:123], v[142:143]
	v_pk_mul_f32 v[218:219], v[120:121], v[140:141]
	v_mul_f32_e32 v240, v133, v133
	v_mul_f32_e32 v241, v135, v135
	v_fmac_f32_e32 v215, v136, v136
	v_fmac_f32_e32 v221, v138, v138
	v_cvt_pk_bf16_f32 v136, v198, v199
	v_cvt_pk_bf16_f32 v137, v196, v197
	v_fmac_f32_e32 v238, v140, v140
	v_fmac_f32_e32 v239, v142, v142
	v_cvt_pk_bf16_f32 v138, v218, v219
	v_cvt_pk_bf16_f32 v139, v216, v217
	v_fmac_f32_e32 v240, v132, v132
	v_fmac_f32_e32 v241, v134, v134
	v_add_f32_e32 v197, v215, v221
	global_store_dwordx2 v[234:235], v[136:137], off
	global_store_dwordx4 v[230:231], v[140:143], off offset:64
	v_add_f32_e32 v136, v238, v239
	v_pk_mul_f32 v[224:225], v[116:117], v[132:133]
	global_store_dwordx2 v[236:237], v[138:139], off
	global_store_dwordx4 v[230:231], v[132:135], off offset:512
	v_pk_mul_f32 v[222:223], v[118:119], v[134:135]
	v_cvt_pk_bf16_f32 v196, v224, v225
	v_add_f32_e32 v132, v240, v241
	v_add_f32_e32 v133, v197, v136
	v_add_f32_e32 v134, v133, v132
	v_or_b32_e32 v132, 0x100, v232
	v_mov_b32_e32 v133, v233
	v_cvt_pk_bf16_f32 v197, v222, v223
	v_lshl_add_u64 v[132:133], s[14:15], 0, v[132:133]
	v_pk_add_f32 v[126:127], v[126:127], v[228:229]
	v_pk_add_f32 v[124:125], v[124:125], v[226:227]
	global_store_dwordx2 v[132:133], v[196:197], off
	v_mul_f32_e32 v132, v125, v125
	v_mul_f32_e32 v133, v127, v127
	v_fmac_f32_e32 v132, v124, v124
	v_fmac_f32_e32 v133, v126, v126
	v_add_f32_e32 v132, v132, v133
	v_add_f32_e32 v133, v134, v132
	ds_bpermute_b32 v134, v214, v133
	global_store_dwordx4 v[230:231], v[124:127], off offset:576
	v_or_b32_e32 v232, 0x120, v232
	s_nop 0
	v_pk_mul_f32 v[124:125], v[112:113], v[124:125]
	v_pk_mul_f32 v[126:127], v[114:115], v[126:127]
	v_cvt_pk_bf16_f32 v132, v124, v125
	s_waitcnt lgkmcnt(0)
	v_add_f32_e32 v124, v133, v134
	ds_bpermute_b32 v125, v213, v124
	v_cvt_pk_bf16_f32 v133, v126, v127
	v_lshl_add_u64 v[126:127], s[14:15], 0, v[232:233]
	global_store_dwordx2 v[126:127], v[132:133], off
	s_and_saveexec_b64 s[28:29], s[2:3]
	s_cbranch_execz .LBB0_854
	v_lshl_add_u64 v[126:127], v[200:201], 2, s[16:17]
	s_waitcnt lgkmcnt(0)
	v_add_f32_e32 v124, v124, v125
	global_atomic_add_f32 v[126:127], v124, off
.LBB0_854:
	s_or_b64 exec, exec, s[28:29]
	v_or_b32_e32 v196, 48, v200
	v_ashrrev_i32_e32 v197, 31, v196
	v_readlane_b32 s60, v252, 16
	s_waitcnt lgkmcnt(0)
	v_lshlrev_b64 v[124:125], 13, v[196:197]
	v_readlane_b32 s74, v252, 30
	v_readlane_b32 s75, v252, 31
	v_pk_add_f32 v[110:111], v[110:111], v[174:175]
	v_pk_add_f32 v[108:109], v[108:109], v[172:173]
	v_lshl_add_u64 v[124:125], s[74:75], 0, v[124:125]
	v_lshl_add_u64 v[198:199], v[188:189], 2, v[124:125]
	global_load_dwordx4 v[140:143], v[198:199], off nt
	global_load_dwordx4 v[136:139], v[198:199], off offset:64 nt
	global_load_dwordx4 v[132:135], v[198:199], off offset:512 nt
	global_load_dwordx4 v[124:127], v[198:199], off offset:576 nt
	v_lshlrev_b64 v[216:217], 11, v[202:203]
	v_mul_f32_e32 v172, v109, v109
	v_mul_f32_e32 v173, v111, v111
	v_lshl_add_u64 v[216:217], v[216:217], 0, v[188:189]
	global_store_dwordx4 v[204:205], v[108:111], off
	v_fmac_f32_e32 v172, v108, v108
	v_fmac_f32_e32 v173, v110, v110
	v_pk_mul_f32 v[110:111], v[130:131], v[110:111]
	v_pk_mul_f32 v[108:109], v[128:129], v[108:109]
	v_add_f32_e32 v174, v172, v173
	v_cvt_pk_bf16_f32 v108, v108, v109
	v_cvt_pk_bf16_f32 v109, v110, v111
	v_lshlrev_b64 v[110:111], 1, v[216:217]
	v_lshl_add_u64 v[172:173], s[14:15], 0, v[110:111]
	v_pk_add_f32 v[106:107], v[106:107], v[170:171]
	v_pk_add_f32 v[104:105], v[104:105], v[168:169]
	global_store_dwordx2 v[172:173], v[108:109], off
	v_mul_f32_e32 v108, v105, v105
	v_mul_f32_e32 v109, v107, v107
	global_store_dwordx4 v[204:205], v[104:107], off offset:64
	v_fmac_f32_e32 v108, v104, v104
	v_fmac_f32_e32 v109, v106, v106
	v_pk_mul_f32 v[106:107], v[122:123], v[106:107]
	v_pk_mul_f32 v[104:105], v[120:121], v[104:105]
	v_pk_add_f32 v[102:103], v[102:103], v[166:167]
	v_cvt_pk_bf16_f32 v104, v104, v105
	v_cvt_pk_bf16_f32 v105, v106, v107
	v_or_b32_e32 v106, 32, v110
	v_mov_b32_e32 v107, v111
	v_lshl_add_u64 v[106:107], s[14:15], 0, v[106:107]
	v_pk_add_f32 v[100:101], v[100:101], v[164:165]
	global_store_dwordx2 v[106:107], v[104:105], off
	v_mul_f32_e32 v104, v101, v101
	v_mul_f32_e32 v105, v103, v103
	global_store_dwordx4 v[204:205], v[100:103], off offset:512
	v_fmac_f32_e32 v104, v100, v100
	v_fmac_f32_e32 v105, v102, v102
	v_pk_mul_f32 v[102:103], v[118:119], v[102:103]
	v_pk_mul_f32 v[100:101], v[116:117], v[100:101]
	v_pk_add_f32 v[98:99], v[98:99], v[162:163]
	v_cvt_pk_bf16_f32 v100, v100, v101
	v_cvt_pk_bf16_f32 v101, v102, v103
	v_or_b32_e32 v102, 0x100, v110
	v_mov_b32_e32 v103, v111
	v_lshl_add_u64 v[102:103], s[14:15], 0, v[102:103]
	v_pk_add_f32 v[96:97], v[96:97], v[160:161]
	v_add_f32_e32 v108, v108, v109
	global_store_dwordx2 v[102:103], v[100:101], off
	v_mul_f32_e32 v100, v97, v97
	v_mul_f32_e32 v101, v99, v99
	v_add_f32_e32 v108, v174, v108
	v_add_f32_e32 v104, v104, v105
	v_fmac_f32_e32 v100, v96, v96
	v_fmac_f32_e32 v101, v98, v98
	v_add_f32_e32 v104, v108, v104
	v_add_f32_e32 v100, v100, v101
	v_add_f32_e32 v101, v104, v100
	ds_bpermute_b32 v102, v214, v101
	global_store_dwordx4 v[204:205], v[96:99], off offset:576
	v_or_b32_e32 v110, 0x120, v110
	v_readlane_b32 s61, v252, 17
	v_pk_mul_f32 v[96:97], v[112:113], v[96:97]
	v_pk_mul_f32 v[98:99], v[114:115], v[98:99]
	v_cvt_pk_bf16_f32 v100, v96, v97
	s_waitcnt lgkmcnt(0)
	v_add_f32_e32 v96, v101, v102
	ds_bpermute_b32 v97, v213, v96
	v_cvt_pk_bf16_f32 v101, v98, v99
	v_lshl_add_u64 v[98:99], s[14:15], 0, v[110:111]
	v_readlane_b32 s62, v252, 18
	v_readlane_b32 s63, v252, 19
	v_readlane_b32 s64, v252, 20
	v_readlane_b32 s65, v252, 21
	v_readlane_b32 s66, v252, 22
	v_readlane_b32 s67, v252, 23
	v_readlane_b32 s68, v252, 24
	v_readlane_b32 s69, v252, 25
	v_readlane_b32 s70, v252, 26
	v_readlane_b32 s71, v252, 27
	v_readlane_b32 s72, v252, 28
	v_readlane_b32 s73, v252, 29
	global_store_dwordx2 v[98:99], v[100:101], off
	s_and_saveexec_b64 s[28:29], s[2:3]
	s_cbranch_execz .LBB0_856
	v_lshl_add_u64 v[98:99], v[202:203], 2, s[16:17]
	s_waitcnt lgkmcnt(0)
	v_add_f32_e32 v96, v96, v97
	global_atomic_add_f32 v[98:99], v96, off
.LBB0_856:
	s_or_b64 exec, exec, s[28:29]
	v_add_u32_e32 v160, 0x80, v200
	v_ashrrev_i32_e32 v161, 31, v160
	v_readlane_b32 s60, v252, 16
	s_waitcnt lgkmcnt(0)
	v_lshlrev_b64 v[96:97], 13, v[160:161]
	v_readlane_b32 s74, v252, 30
	v_readlane_b32 s75, v252, 31
	v_pk_add_f32 v[94:95], v[94:95], v[158:159]
	v_pk_add_f32 v[92:93], v[92:93], v[156:157]
	v_lshl_add_u64 v[96:97], s[74:75], 0, v[96:97]
	v_lshl_add_u64 v[162:163], v[188:189], 2, v[96:97]
	global_load_dwordx4 v[108:111], v[162:163], off nt
	global_load_dwordx4 v[104:107], v[162:163], off offset:64 nt
	global_load_dwordx4 v[100:103], v[162:163], off offset:512 nt
	global_load_dwordx4 v[96:99], v[162:163], off offset:576 nt
	v_lshlrev_b64 v[164:165], 11, v[192:193]
	v_mul_f32_e32 v156, v93, v93
	v_mul_f32_e32 v157, v95, v95
	v_lshl_add_u64 v[164:165], v[164:165], 0, v[188:189]
	global_store_dwordx4 v[194:195], v[92:95], off
	v_fmac_f32_e32 v156, v92, v92
	v_fmac_f32_e32 v157, v94, v94
	v_pk_mul_f32 v[94:95], v[130:131], v[94:95]
	v_pk_mul_f32 v[92:93], v[128:129], v[92:93]
	v_add_f32_e32 v158, v156, v157
	v_cvt_pk_bf16_f32 v92, v92, v93
	v_cvt_pk_bf16_f32 v93, v94, v95
	v_lshlrev_b64 v[94:95], 1, v[164:165]
	v_lshl_add_u64 v[156:157], s[14:15], 0, v[94:95]
	v_pk_add_f32 v[90:91], v[90:91], v[154:155]
	v_pk_add_f32 v[88:89], v[88:89], v[152:153]
	global_store_dwordx2 v[156:157], v[92:93], off
	v_mul_f32_e32 v92, v89, v89
	v_mul_f32_e32 v93, v91, v91
	global_store_dwordx4 v[194:195], v[88:91], off offset:64
	v_fmac_f32_e32 v92, v88, v88
	v_fmac_f32_e32 v93, v90, v90
	v_pk_mul_f32 v[90:91], v[122:123], v[90:91]
	v_pk_mul_f32 v[88:89], v[120:121], v[88:89]
	v_pk_add_f32 v[86:87], v[86:87], v[150:151]
	v_cvt_pk_bf16_f32 v88, v88, v89
	v_cvt_pk_bf16_f32 v89, v90, v91
	v_or_b32_e32 v90, 32, v94
	v_mov_b32_e32 v91, v95
	v_lshl_add_u64 v[90:91], s[14:15], 0, v[90:91]
	v_pk_add_f32 v[84:85], v[84:85], v[148:149]
	global_store_dwordx2 v[90:91], v[88:89], off
	v_mul_f32_e32 v88, v85, v85
	v_mul_f32_e32 v89, v87, v87
	global_store_dwordx4 v[194:195], v[84:87], off offset:512
	v_fmac_f32_e32 v88, v84, v84
	v_fmac_f32_e32 v89, v86, v86
	v_pk_mul_f32 v[86:87], v[118:119], v[86:87]
	v_pk_mul_f32 v[84:85], v[116:117], v[84:85]
	v_pk_add_f32 v[82:83], v[82:83], v[146:147]
	v_cvt_pk_bf16_f32 v84, v84, v85
	v_cvt_pk_bf16_f32 v85, v86, v87
	v_or_b32_e32 v86, 0x100, v94
	v_mov_b32_e32 v87, v95
	v_lshl_add_u64 v[86:87], s[14:15], 0, v[86:87]
	v_pk_add_f32 v[80:81], v[80:81], v[144:145]
	v_add_f32_e32 v92, v92, v93
	global_store_dwordx2 v[86:87], v[84:85], off
	v_mul_f32_e32 v84, v81, v81
	v_mul_f32_e32 v85, v83, v83
	v_add_f32_e32 v92, v158, v92
	v_add_f32_e32 v88, v88, v89
	v_fmac_f32_e32 v84, v80, v80
	v_fmac_f32_e32 v85, v82, v82
	v_add_f32_e32 v88, v92, v88
	v_add_f32_e32 v84, v84, v85
	v_add_f32_e32 v85, v88, v84
	ds_bpermute_b32 v86, v214, v85
	global_store_dwordx4 v[194:195], v[80:83], off offset:576
	v_or_b32_e32 v94, 0x120, v94
	v_readlane_b32 s61, v252, 17
	v_pk_mul_f32 v[80:81], v[112:113], v[80:81]
	v_pk_mul_f32 v[82:83], v[114:115], v[82:83]
	v_cvt_pk_bf16_f32 v84, v80, v81
	s_waitcnt lgkmcnt(0)
	v_add_f32_e32 v80, v85, v86
	ds_bpermute_b32 v81, v213, v80
	v_cvt_pk_bf16_f32 v85, v82, v83
	v_lshl_add_u64 v[82:83], s[14:15], 0, v[94:95]
	v_readlane_b32 s62, v252, 18
	v_readlane_b32 s63, v252, 19
	v_readlane_b32 s64, v252, 20
	v_readlane_b32 s65, v252, 21
	v_readlane_b32 s66, v252, 22
	v_readlane_b32 s67, v252, 23
	v_readlane_b32 s68, v252, 24
	v_readlane_b32 s69, v252, 25
	v_readlane_b32 s70, v252, 26
	v_readlane_b32 s71, v252, 27
	v_readlane_b32 s72, v252, 28
	v_readlane_b32 s73, v252, 29
	global_store_dwordx2 v[82:83], v[84:85], off
	s_and_saveexec_b64 s[28:29], s[2:3]
	s_cbranch_execz .LBB0_858
	v_lshl_add_u64 v[82:83], v[192:193], 2, s[16:17]
	s_waitcnt lgkmcnt(0)
	v_add_f32_e32 v80, v80, v81
	global_atomic_add_f32 v[82:83], v80, off
.LBB0_858:
	s_or_b64 exec, exec, s[28:29]
	s_waitcnt lgkmcnt(0)
	v_lshl_add_u64 v[80:81], v[188:189], 2, v[190:191]
	v_lshl_add_u64 v[144:145], v[80:81], 0, s[24:25]
	v_add_co_u32_e32 v80, vcc, 0x120000, v80
	s_waitcnt vmcnt(23)
	v_pk_add_f32 v[78:79], v[78:79], v[142:143]
	v_addc_co_u32_e32 v81, vcc, 0, v81, vcc
	global_load_dwordx4 v[88:91], v[144:145], off offset:64 nt
	global_load_dwordx4 v[84:87], v[144:145], off offset:512 nt
	global_load_dwordx4 v[92:95], v[80:81], off nt
	s_nop 0
	global_load_dwordx4 v[80:83], v[144:145], off offset:576 nt
	v_pk_add_f32 v[76:77], v[76:77], v[140:141]
	v_lshlrev_b64 v[146:147], 11, v[196:197]
	v_mul_f32_e32 v140, v77, v77
	v_mul_f32_e32 v141, v79, v79
	v_lshl_add_u64 v[146:147], v[146:147], 0, v[188:189]
	global_store_dwordx4 v[198:199], v[76:79], off
	v_fmac_f32_e32 v140, v76, v76
	v_fmac_f32_e32 v141, v78, v78
	v_pk_mul_f32 v[78:79], v[130:131], v[78:79]
	v_pk_mul_f32 v[76:77], v[128:129], v[76:77]
	v_add_f32_e32 v142, v140, v141
	v_cvt_pk_bf16_f32 v76, v76, v77
	v_cvt_pk_bf16_f32 v77, v78, v79
	v_lshlrev_b64 v[78:79], 1, v[146:147]
	v_lshl_add_u64 v[140:141], s[14:15], 0, v[78:79]
	s_waitcnt vmcnt(27)
	v_pk_add_f32 v[74:75], v[74:75], v[138:139]
	v_pk_add_f32 v[72:73], v[72:73], v[136:137]
	global_store_dwordx2 v[140:141], v[76:77], off
	v_mul_f32_e32 v76, v73, v73
	v_mul_f32_e32 v77, v75, v75
	global_store_dwordx4 v[198:199], v[72:75], off offset:64
	v_fmac_f32_e32 v76, v72, v72
	v_fmac_f32_e32 v77, v74, v74
	v_pk_mul_f32 v[74:75], v[122:123], v[74:75]
	v_pk_mul_f32 v[72:73], v[120:121], v[72:73]
	s_waitcnt vmcnt(28)
	v_pk_add_f32 v[70:71], v[70:71], v[134:135]
	v_cvt_pk_bf16_f32 v72, v72, v73
	v_cvt_pk_bf16_f32 v73, v74, v75
	v_or_b32_e32 v74, 32, v78
	v_mov_b32_e32 v75, v79
	v_lshl_add_u64 v[74:75], s[14:15], 0, v[74:75]
	v_pk_add_f32 v[68:69], v[68:69], v[132:133]
	global_store_dwordx2 v[74:75], v[72:73], off
	v_mul_f32_e32 v72, v69, v69
	v_mul_f32_e32 v73, v71, v71
	global_store_dwordx4 v[198:199], v[68:71], off offset:512
	v_fmac_f32_e32 v72, v68, v68
	v_fmac_f32_e32 v73, v70, v70
	v_pk_mul_f32 v[70:71], v[118:119], v[70:71]
	v_pk_mul_f32 v[68:69], v[116:117], v[68:69]
	s_waitcnt vmcnt(29)
	v_pk_add_f32 v[66:67], v[66:67], v[126:127]
	v_cvt_pk_bf16_f32 v68, v68, v69
	v_cvt_pk_bf16_f32 v69, v70, v71
	v_or_b32_e32 v70, 0x100, v78
	v_mov_b32_e32 v71, v79
	v_lshl_add_u64 v[70:71], s[14:15], 0, v[70:71]
	v_pk_add_f32 v[64:65], v[64:65], v[124:125]
	v_add_f32_e32 v76, v76, v77
	global_store_dwordx2 v[70:71], v[68:69], off
	v_mul_f32_e32 v68, v65, v65
	v_mul_f32_e32 v69, v67, v67
	v_add_f32_e32 v76, v142, v76
	v_add_f32_e32 v72, v72, v73
	v_fmac_f32_e32 v68, v64, v64
	v_fmac_f32_e32 v69, v66, v66
	v_add_f32_e32 v72, v76, v72
	v_add_f32_e32 v68, v68, v69
	v_add_f32_e32 v69, v72, v68
	ds_bpermute_b32 v70, v214, v69
	global_store_dwordx4 v[198:199], v[64:67], off offset:576
	v_or_b32_e32 v78, 0x120, v78
	s_nop 0
	v_pk_mul_f32 v[64:65], v[112:113], v[64:65]
	v_pk_mul_f32 v[66:67], v[114:115], v[66:67]
	v_cvt_pk_bf16_f32 v68, v64, v65
	s_waitcnt lgkmcnt(0)
	v_add_f32_e32 v64, v69, v70
	ds_bpermute_b32 v65, v213, v64
	v_cvt_pk_bf16_f32 v69, v66, v67
	v_lshl_add_u64 v[66:67], s[14:15], 0, v[78:79]
	global_store_dwordx2 v[66:67], v[68:69], off
	s_and_saveexec_b64 s[28:29], s[2:3]
	s_cbranch_execz .LBB0_860
	v_lshl_add_u64 v[66:67], v[196:197], 2, s[16:17]
	s_waitcnt lgkmcnt(0)
	v_add_f32_e32 v64, v64, v65
	global_atomic_add_f32 v[66:67], v64, off
.LBB0_860:
	s_or_b64 exec, exec, s[28:29]
	v_or_b32_e32 v124, 32, v160
	v_ashrrev_i32_e32 v125, 31, v124
	v_readlane_b32 s60, v252, 16
	s_waitcnt lgkmcnt(0)
	v_lshlrev_b64 v[64:65], 13, v[124:125]
	v_readlane_b32 s74, v252, 30
	v_readlane_b32 s75, v252, 31
	s_waitcnt vmcnt(23)
	v_pk_add_f32 v[62:63], v[62:63], v[110:111]
	v_pk_add_f32 v[60:61], v[60:61], v[108:109]
	v_lshl_add_u64 v[64:65], s[74:75], 0, v[64:65]
	v_lshl_add_u64 v[126:127], v[188:189], 2, v[64:65]
	global_load_dwordx4 v[76:79], v[126:127], off nt
	global_load_dwordx4 v[72:75], v[126:127], off offset:64 nt
	global_load_dwordx4 v[68:71], v[126:127], off offset:512 nt
	global_load_dwordx4 v[64:67], v[126:127], off offset:576 nt
	v_lshlrev_b64 v[132:133], 11, v[160:161]
	v_mul_f32_e32 v108, v61, v61
	v_mul_f32_e32 v109, v63, v63
	v_lshl_add_u64 v[132:133], v[132:133], 0, v[188:189]
	global_store_dwordx4 v[162:163], v[60:63], off
	v_fmac_f32_e32 v108, v60, v60
	v_fmac_f32_e32 v109, v62, v62
	v_pk_mul_f32 v[62:63], v[130:131], v[62:63]
	v_pk_mul_f32 v[60:61], v[128:129], v[60:61]
	v_add_f32_e32 v110, v108, v109
	v_cvt_pk_bf16_f32 v60, v60, v61
	v_cvt_pk_bf16_f32 v61, v62, v63
	v_lshlrev_b64 v[62:63], 1, v[132:133]
	v_lshl_add_u64 v[108:109], s[14:15], 0, v[62:63]
	s_waitcnt vmcnt(27)
	v_pk_add_f32 v[58:59], v[58:59], v[106:107]
	v_pk_add_f32 v[56:57], v[56:57], v[104:105]
	global_store_dwordx2 v[108:109], v[60:61], off
	v_mul_f32_e32 v60, v57, v57
	v_mul_f32_e32 v61, v59, v59
	global_store_dwordx4 v[162:163], v[56:59], off offset:64
	v_fmac_f32_e32 v60, v56, v56
	v_fmac_f32_e32 v61, v58, v58
	v_pk_mul_f32 v[58:59], v[122:123], v[58:59]
	v_pk_mul_f32 v[56:57], v[120:121], v[56:57]
	s_waitcnt vmcnt(28)
	v_pk_add_f32 v[54:55], v[54:55], v[102:103]
	v_cvt_pk_bf16_f32 v56, v56, v57
	v_cvt_pk_bf16_f32 v57, v58, v59
	v_or_b32_e32 v58, 32, v62
	v_mov_b32_e32 v59, v63
	v_lshl_add_u64 v[58:59], s[14:15], 0, v[58:59]
	v_pk_add_f32 v[52:53], v[52:53], v[100:101]
	global_store_dwordx2 v[58:59], v[56:57], off
	v_mul_f32_e32 v56, v53, v53
	v_mul_f32_e32 v57, v55, v55
	global_store_dwordx4 v[162:163], v[52:55], off offset:512
	v_fmac_f32_e32 v56, v52, v52
	v_fmac_f32_e32 v57, v54, v54
	v_pk_mul_f32 v[54:55], v[118:119], v[54:55]
	v_pk_mul_f32 v[52:53], v[116:117], v[52:53]
	s_waitcnt vmcnt(29)
	v_pk_add_f32 v[50:51], v[50:51], v[98:99]
	v_cvt_pk_bf16_f32 v52, v52, v53
	v_cvt_pk_bf16_f32 v53, v54, v55
	v_or_b32_e32 v54, 0x100, v62
	v_mov_b32_e32 v55, v63
	v_lshl_add_u64 v[54:55], s[14:15], 0, v[54:55]
	v_pk_add_f32 v[48:49], v[48:49], v[96:97]
	v_add_f32_e32 v60, v60, v61
	global_store_dwordx2 v[54:55], v[52:53], off
	v_mul_f32_e32 v52, v49, v49
	v_mul_f32_e32 v53, v51, v51
	v_add_f32_e32 v60, v110, v60
	v_add_f32_e32 v56, v56, v57
	v_fmac_f32_e32 v52, v48, v48
	v_fmac_f32_e32 v53, v50, v50
	v_add_f32_e32 v56, v60, v56
	v_add_f32_e32 v52, v52, v53
	v_add_f32_e32 v53, v56, v52
	ds_bpermute_b32 v54, v214, v53
	global_store_dwordx4 v[162:163], v[48:51], off offset:576
	v_or_b32_e32 v62, 0x120, v62
	v_readlane_b32 s61, v252, 17
	v_pk_mul_f32 v[48:49], v[112:113], v[48:49]
	v_pk_mul_f32 v[50:51], v[114:115], v[50:51]
	v_cvt_pk_bf16_f32 v52, v48, v49
	s_waitcnt lgkmcnt(0)
	v_add_f32_e32 v48, v53, v54
	ds_bpermute_b32 v49, v213, v48
	v_cvt_pk_bf16_f32 v53, v50, v51
	v_lshl_add_u64 v[50:51], s[14:15], 0, v[62:63]
	v_readlane_b32 s62, v252, 18
	v_readlane_b32 s63, v252, 19
	v_readlane_b32 s64, v252, 20
	v_readlane_b32 s65, v252, 21
	v_readlane_b32 s66, v252, 22
	v_readlane_b32 s67, v252, 23
	v_readlane_b32 s68, v252, 24
	v_readlane_b32 s69, v252, 25
	v_readlane_b32 s70, v252, 26
	v_readlane_b32 s71, v252, 27
	v_readlane_b32 s72, v252, 28
	v_readlane_b32 s73, v252, 29
	global_store_dwordx2 v[50:51], v[52:53], off
	s_and_saveexec_b64 s[28:29], s[2:3]
	s_cbranch_execz .LBB0_862
	v_lshl_add_u64 v[50:51], v[160:161], 2, s[16:17]
	s_waitcnt lgkmcnt(0)
	v_add_f32_e32 v48, v48, v49
	global_atomic_add_f32 v[50:51], v48, off
.LBB0_862:
	s_or_b64 exec, exec, s[28:29]
	v_or_b32_e32 v96, 48, v160
	v_ashrrev_i32_e32 v97, 31, v96
	v_readlane_b32 s60, v252, 16
	s_waitcnt lgkmcnt(0)
	v_lshlrev_b64 v[48:49], 13, v[96:97]
	v_readlane_b32 s74, v252, 30
	v_readlane_b32 s75, v252, 31
	v_or_b32_e32 v100, 16, v160
	v_ashrrev_i32_e32 v101, 31, v100
	v_lshl_add_u64 v[48:49], s[74:75], 0, v[48:49]
	v_lshl_add_u64 v[98:99], v[188:189], 2, v[48:49]
	global_load_dwordx4 v[60:63], v[98:99], off nt
	global_load_dwordx4 v[56:59], v[98:99], off offset:64 nt
	global_load_dwordx4 v[52:55], v[98:99], off offset:512 nt
	global_load_dwordx4 v[48:51], v[98:99], off offset:576 nt
	s_waitcnt vmcnt(25)
	v_pk_add_f32 v[46:47], v[46:47], v[94:95]
	v_pk_add_f32 v[44:45], v[44:45], v[92:93]
	v_lshlrev_b64 v[102:103], 11, v[100:101]
	v_mul_f32_e32 v92, v45, v45
	v_mul_f32_e32 v93, v47, v47
	v_lshl_add_u64 v[102:103], v[102:103], 0, v[188:189]
	global_store_dwordx4 v[144:145], v[44:47], off
	v_fmac_f32_e32 v92, v44, v44
	v_fmac_f32_e32 v93, v46, v46
	v_pk_mul_f32 v[46:47], v[130:131], v[46:47]
	v_pk_mul_f32 v[44:45], v[128:129], v[44:45]
	v_add_f32_e32 v94, v92, v93
	v_cvt_pk_bf16_f32 v44, v44, v45
	v_cvt_pk_bf16_f32 v45, v46, v47
	v_lshlrev_b64 v[46:47], 1, v[102:103]
	v_lshl_add_u64 v[92:93], s[14:15], 0, v[46:47]
	v_pk_add_f32 v[42:43], v[42:43], v[90:91]
	v_pk_add_f32 v[40:41], v[40:41], v[88:89]
	global_store_dwordx2 v[92:93], v[44:45], off
	v_mul_f32_e32 v44, v41, v41
	v_mul_f32_e32 v45, v43, v43
	global_store_dwordx4 v[144:145], v[40:43], off offset:64
	v_fmac_f32_e32 v44, v40, v40
	v_fmac_f32_e32 v45, v42, v42
	v_pk_mul_f32 v[42:43], v[122:123], v[42:43]
	v_pk_mul_f32 v[40:41], v[120:121], v[40:41]
	v_pk_add_f32 v[38:39], v[38:39], v[86:87]
	v_cvt_pk_bf16_f32 v40, v40, v41
	v_cvt_pk_bf16_f32 v41, v42, v43
	v_or_b32_e32 v42, 32, v46
	v_mov_b32_e32 v43, v47
	v_lshl_add_u64 v[42:43], s[14:15], 0, v[42:43]
	v_pk_add_f32 v[36:37], v[36:37], v[84:85]
	global_store_dwordx2 v[42:43], v[40:41], off
	v_mul_f32_e32 v40, v37, v37
	v_mul_f32_e32 v41, v39, v39
	global_store_dwordx4 v[144:145], v[36:39], off offset:512
	v_fmac_f32_e32 v40, v36, v36
	v_fmac_f32_e32 v41, v38, v38
	v_pk_mul_f32 v[38:39], v[118:119], v[38:39]
	v_pk_mul_f32 v[36:37], v[116:117], v[36:37]
	s_waitcnt vmcnt(29)
	v_pk_add_f32 v[34:35], v[34:35], v[82:83]
	v_cvt_pk_bf16_f32 v36, v36, v37
	v_cvt_pk_bf16_f32 v37, v38, v39
	v_or_b32_e32 v38, 0x100, v46
	v_mov_b32_e32 v39, v47
	v_lshl_add_u64 v[38:39], s[14:15], 0, v[38:39]
	v_pk_add_f32 v[32:33], v[32:33], v[80:81]
	v_add_f32_e32 v44, v44, v45
	global_store_dwordx2 v[38:39], v[36:37], off
	v_mul_f32_e32 v36, v33, v33
	v_mul_f32_e32 v37, v35, v35
	v_add_f32_e32 v44, v94, v44
	v_add_f32_e32 v40, v40, v41
	v_fmac_f32_e32 v36, v32, v32
	v_fmac_f32_e32 v37, v34, v34
	v_add_f32_e32 v40, v44, v40
	v_add_f32_e32 v36, v36, v37
	v_add_f32_e32 v37, v40, v36
	ds_bpermute_b32 v38, v214, v37
	global_store_dwordx4 v[144:145], v[32:35], off offset:576
	v_or_b32_e32 v46, 0x120, v46
	v_readlane_b32 s61, v252, 17
	v_pk_mul_f32 v[32:33], v[112:113], v[32:33]
	v_pk_mul_f32 v[34:35], v[114:115], v[34:35]
	v_cvt_pk_bf16_f32 v36, v32, v33
	s_waitcnt lgkmcnt(0)
	v_add_f32_e32 v32, v37, v38
	ds_bpermute_b32 v33, v213, v32
	v_cvt_pk_bf16_f32 v37, v34, v35
	v_lshl_add_u64 v[34:35], s[14:15], 0, v[46:47]
	v_readlane_b32 s62, v252, 18
	v_readlane_b32 s63, v252, 19
	v_readlane_b32 s64, v252, 20
	v_readlane_b32 s65, v252, 21
	v_readlane_b32 s66, v252, 22
	v_readlane_b32 s67, v252, 23
	v_readlane_b32 s68, v252, 24
	v_readlane_b32 s69, v252, 25
	v_readlane_b32 s70, v252, 26
	v_readlane_b32 s71, v252, 27
	v_readlane_b32 s72, v252, 28
	v_readlane_b32 s73, v252, 29
	global_store_dwordx2 v[34:35], v[36:37], off
	s_and_saveexec_b64 s[28:29], s[2:3]
	s_cbranch_execz .LBB0_864
	v_lshl_add_u64 v[34:35], v[100:101], 2, s[16:17]
	s_waitcnt lgkmcnt(0)
	v_add_f32_e32 v32, v32, v33
	global_atomic_add_f32 v[34:35], v32, off

.LBB0_1060:
	v_readlane_b32 s60, v252, 16
	v_lshl_add_u32 v64, s54, 8, v218
	v_readlane_b32 s61, v252, 17
	v_readlane_b32 s62, v252, 18
	v_readlane_b32 s63, v252, 19
	v_readlane_b32 s72, v252, 28
	v_readlane_b32 s73, v252, 29
	v_lshl_or_b32 v144, s55, 8, v221
	v_ashrrev_i32_e32 v65, 31, v64
	v_readlane_b32 s74, v252, 30
	v_readlane_b32 s75, v252, 31
	s_mov_b64 s[60:61], s[72:73]
	v_ashrrev_i32_e32 v145, 31, v144
	s_waitcnt lgkmcnt(0)
	v_lshlrev_b64 v[0:1], 13, v[64:65]
	s_mov_b64 s[62:63], s[74:75]
	v_lshlrev_b64 v[16:17], 2, v[144:145]
	v_lshl_add_u64 v[210:211], s[62:63], 0, v[0:1]
	v_readlane_b32 s66, v252, 22
	v_readlane_b32 s67, v252, 23
	v_lshl_add_u64 v[228:229], v[210:211], 0, v[16:17]
	s_mov_b64 s[54:55], s[66:67]
	global_load_dwordx4 v[28:31], v[228:229], off nt
	global_load_dwordx4 v[40:43], v[228:229], off offset:64 nt
	global_load_dwordx4 v[52:55], v[228:229], off offset:512 nt
	v_lshl_add_u64 v[0:1], s[54:55], 0, v[16:17]
	global_load_dwordx4 v[12:15], v[0:1], off
	global_load_dwordx4 v[8:11], v[0:1], off offset:64
	global_load_dwordx4 v[4:7], v[0:1], off offset:512
	global_load_dwordx4 v[60:63], v[228:229], off offset:576 nt
	v_or_b32_e32 v66, 16, v64
	v_or_b32_e32 v212, 32, v64
	v_ashrrev_i32_e32 v67, 31, v66
	v_ashrrev_i32_e32 v213, 31, v212
	v_lshlrev_b64 v[18:19], 13, v[66:67]
	v_lshlrev_b64 v[20:21], 13, v[212:213]
	v_lshl_add_u64 v[18:19], s[62:63], 0, v[18:19]
	global_load_dwordx4 v[0:3], v[0:1], off offset:576
	v_lshl_add_u64 v[20:21], s[62:63], 0, v[20:21]
	v_lshl_add_u64 v[216:217], v[18:19], 0, v[16:17]
	v_lshl_add_u64 v[214:215], v[20:21], 0, v[16:17]
	global_load_dwordx4 v[56:59], v[216:217], off nt
	global_load_dwordx4 v[48:51], v[216:217], off offset:64 nt
	global_load_dwordx4 v[36:39], v[216:217], off offset:512 nt
	global_load_dwordx4 v[24:27], v[216:217], off offset:576 nt
	global_load_dwordx4 v[44:47], v[214:215], off nt
	global_load_dwordx4 v[32:35], v[214:215], off offset:64 nt
	global_load_dwordx4 v[20:23], v[214:215], off offset:512 nt
	global_load_dwordx4 v[16:19], v[214:215], off offset:576 nt
	v_and_b32_e32 v227, 64, v225
	v_xor_b32_e32 v226, 16, v225
	v_add_u32_e32 v227, 64, v227
	v_xor_b32_e32 v230, 32, v225
	v_cmp_lt_i32_e32 vcc, v226, v227
	v_readlane_b32 s64, v252, 20
	v_readlane_b32 s65, v252, 21
	v_cndmask_b32_e32 v226, v225, v226, vcc
	v_cmp_lt_i32_e32 vcc, v230, v227
	v_lshlrev_b32_e32 v227, 2, v226
	v_readlane_b32 s68, v252, 24
	v_cndmask_b32_e32 v232, v225, v230, vcc
	v_lshlrev_b64 v[230:231], 11, v[64:65]
	v_lshl_add_u64 v[230:231], v[230:231], 0, v[144:145]
	v_lshlrev_b64 v[230:231], 1, v[230:231]
	v_lshlrev_b32_e32 v226, 2, v232
	v_lshl_add_u64 v[232:233], s[12:13], 0, v[230:231]
	v_or_b32_e32 v234, 32, v230
	v_mov_b32_e32 v235, v231
	v_lshl_add_u64 v[234:235], s[12:13], 0, v[234:235]
	v_readlane_b32 s69, v252, 25
	v_readlane_b32 s70, v252, 26
	v_readlane_b32 s71, v252, 27
	s_waitcnt vmcnt(0)
	v_pk_add_f32 v[30:31], v[198:199], v[30:31]
	v_pk_add_f32 v[28:29], v[200:201], v[28:29]
	v_pk_add_f32 v[42:43], v[202:203], v[42:43]
	v_pk_add_f32 v[40:41], v[204:205], v[40:41]
	v_pk_add_f32 v[54:55], v[208:209], v[54:55]
	v_pk_add_f32 v[52:53], v[206:207], v[52:53]
	v_mul_f32_e32 v236, v29, v29
	v_mul_f32_e32 v237, v31, v31
	v_pk_mul_f32 v[198:199], v[14:15], v[30:31]
	v_pk_mul_f32 v[200:201], v[12:13], v[28:29]
	v_mul_f32_e32 v238, v41, v41
	v_mul_f32_e32 v239, v43, v43
	global_store_dwordx4 v[228:229], v[28:31], off
	v_mul_f32_e32 v240, v53, v53
	v_mul_f32_e32 v241, v55, v55
	v_fmac_f32_e32 v236, v28, v28
	v_fmac_f32_e32 v237, v30, v30
	v_cvt_pk_bf16_f32 v28, v200, v201
	v_cvt_pk_bf16_f32 v29, v198, v199
	v_fmac_f32_e32 v238, v40, v40
	v_fmac_f32_e32 v239, v42, v42
	v_fmac_f32_e32 v240, v52, v52
	v_fmac_f32_e32 v241, v54, v54
	v_add_f32_e32 v199, v236, v237
	global_store_dwordx2 v[232:233], v[28:29], off
	global_store_dwordx4 v[228:229], v[40:43], off offset:64
	v_add_f32_e32 v28, v238, v239
	v_add_f32_e32 v29, v240, v241
	v_add_f32_e32 v28, v199, v28
	v_pk_mul_f32 v[202:203], v[10:11], v[42:43]
	v_pk_mul_f32 v[204:205], v[8:9], v[40:41]
	v_pk_mul_f32 v[206:207], v[6:7], v[54:55]
	v_pk_mul_f32 v[208:209], v[4:5], v[52:53]
	v_add_f32_e32 v40, v28, v29
	v_or_b32_e32 v28, 0x100, v230
	v_mov_b32_e32 v29, v231
	v_cvt_pk_bf16_f32 v30, v204, v205
	v_cvt_pk_bf16_f32 v31, v202, v203
	v_cvt_pk_bf16_f32 v198, v208, v209
	v_cvt_pk_bf16_f32 v199, v206, v207
	v_lshl_add_u64 v[28:29], s[12:13], 0, v[28:29]
	global_store_dwordx2 v[234:235], v[30:31], off
	global_store_dwordx4 v[228:229], v[52:55], off offset:512
	global_store_dwordx2 v[28:29], v[198:199], off
	v_pk_add_f32 v[30:31], v[196:197], v[62:63]
	v_pk_add_f32 v[28:29], v[194:195], v[60:61]
	v_mul_f32_e32 v42, v31, v31
	v_mul_f32_e32 v41, v29, v29
	v_fmac_f32_e32 v41, v28, v28
	v_fmac_f32_e32 v42, v30, v30
	v_add_f32_e32 v41, v41, v42
	v_add_f32_e32 v41, v40, v41
	ds_bpermute_b32 v42, v227, v41
	global_store_dwordx4 v[228:229], v[28:31], off offset:576
	v_or_b32_e32 v230, 0x120, v230
	s_nop 0
	v_pk_mul_f32 v[28:29], v[0:1], v[28:29]
	v_pk_mul_f32 v[30:31], v[2:3], v[30:31]
	v_cvt_pk_bf16_f32 v40, v28, v29
	s_waitcnt lgkmcnt(0)
	v_add_f32_e32 v28, v41, v42
	ds_bpermute_b32 v29, v226, v28
	v_cvt_pk_bf16_f32 v41, v30, v31
	v_lshl_add_u64 v[30:31], s[12:13], 0, v[230:231]
	global_store_dwordx2 v[30:31], v[40:41], off
	s_and_saveexec_b64 s[24:25], s[2:3]
	s_cbranch_execz .LBB0_1062
	v_lshl_add_u64 v[30:31], v[64:65], 2, s[14:15]
	s_waitcnt lgkmcnt(0)
	v_add_f32_e32 v28, v28, v29
	global_atomic_add_f32 v[30:31], v28, off
.LBB0_1062:
	s_or_b64 exec, exec, s[24:25]
	v_or_b32_e32 v194, 48, v64
	v_ashrrev_i32_e32 v195, 31, v194
	v_readlane_b32 s60, v252, 16
	s_waitcnt lgkmcnt(0)
	v_lshlrev_b64 v[28:29], 13, v[194:195]
	v_readlane_b32 s74, v252, 30
	v_readlane_b32 s75, v252, 31
	v_pk_add_f32 v[58:59], v[192:193], v[58:59]
	v_pk_add_f32 v[56:57], v[190:191], v[56:57]
	v_lshl_add_u64 v[28:29], s[74:75], 0, v[28:29]
	v_lshl_add_u64 v[196:197], v[144:145], 2, v[28:29]
	global_load_dwordx4 v[60:63], v[196:197], off nt
	global_load_dwordx4 v[52:55], v[196:197], off offset:64 nt
	global_load_dwordx4 v[40:43], v[196:197], off offset:512 nt
	global_load_dwordx4 v[28:31], v[196:197], off offset:576 nt
	v_lshlrev_b64 v[198:199], 11, v[66:67]
	v_mul_f32_e32 v65, v57, v57
	v_mul_f32_e32 v190, v59, v59
	v_lshl_add_u64 v[198:199], v[198:199], 0, v[144:145]
	global_store_dwordx4 v[216:217], v[56:59], off
	v_fmac_f32_e32 v65, v56, v56
	v_fmac_f32_e32 v190, v58, v58
	v_pk_mul_f32 v[58:59], v[14:15], v[58:59]
	v_pk_mul_f32 v[56:57], v[12:13], v[56:57]
	v_add_f32_e32 v65, v65, v190
	v_cvt_pk_bf16_f32 v56, v56, v57
	v_cvt_pk_bf16_f32 v57, v58, v59
	v_lshlrev_b64 v[58:59], 1, v[198:199]
	v_lshl_add_u64 v[190:191], s[12:13], 0, v[58:59]
	v_pk_add_f32 v[50:51], v[188:189], v[50:51]
	v_pk_add_f32 v[48:49], v[186:187], v[48:49]
	global_store_dwordx2 v[190:191], v[56:57], off
	v_mul_f32_e32 v56, v49, v49
	v_mul_f32_e32 v57, v51, v51
	global_store_dwordx4 v[216:217], v[48:51], off offset:64
	v_fmac_f32_e32 v56, v48, v48
	v_fmac_f32_e32 v57, v50, v50
	v_pk_mul_f32 v[50:51], v[10:11], v[50:51]
	v_pk_mul_f32 v[48:49], v[8:9], v[48:49]
	v_pk_add_f32 v[38:39], v[184:185], v[38:39]
	v_cvt_pk_bf16_f32 v48, v48, v49
	v_cvt_pk_bf16_f32 v49, v50, v51
	v_or_b32_e32 v50, 32, v58
	v_mov_b32_e32 v51, v59
	v_lshl_add_u64 v[50:51], s[12:13], 0, v[50:51]
	v_pk_add_f32 v[36:37], v[182:183], v[36:37]
	global_store_dwordx2 v[50:51], v[48:49], off
	v_mul_f32_e32 v48, v37, v37
	v_mul_f32_e32 v49, v39, v39
	global_store_dwordx4 v[216:217], v[36:39], off offset:512
	v_fmac_f32_e32 v48, v36, v36
	v_fmac_f32_e32 v49, v38, v38
	v_pk_mul_f32 v[38:39], v[6:7], v[38:39]
	v_pk_mul_f32 v[36:37], v[4:5], v[36:37]
	v_pk_add_f32 v[26:27], v[180:181], v[26:27]
	v_cvt_pk_bf16_f32 v36, v36, v37
	v_cvt_pk_bf16_f32 v37, v38, v39
	v_or_b32_e32 v38, 0x100, v58
	v_mov_b32_e32 v39, v59
	v_lshl_add_u64 v[38:39], s[12:13], 0, v[38:39]
	v_pk_add_f32 v[24:25], v[178:179], v[24:25]
	v_add_f32_e32 v56, v56, v57
	global_store_dwordx2 v[38:39], v[36:37], off
	v_mul_f32_e32 v36, v25, v25
	v_mul_f32_e32 v37, v27, v27
	v_add_f32_e32 v56, v65, v56
	v_add_f32_e32 v48, v48, v49
	v_fmac_f32_e32 v36, v24, v24
	v_fmac_f32_e32 v37, v26, v26
	v_add_f32_e32 v48, v56, v48
	v_add_f32_e32 v36, v36, v37
	v_add_f32_e32 v37, v48, v36
	ds_bpermute_b32 v38, v227, v37
	global_store_dwordx4 v[216:217], v[24:27], off offset:576
	v_or_b32_e32 v58, 0x120, v58
	v_readlane_b32 s61, v252, 17
	v_pk_mul_f32 v[24:25], v[0:1], v[24:25]
	v_pk_mul_f32 v[26:27], v[2:3], v[26:27]
	v_cvt_pk_bf16_f32 v36, v24, v25
	s_waitcnt lgkmcnt(0)
	v_add_f32_e32 v24, v37, v38
	ds_bpermute_b32 v25, v226, v24
	v_cvt_pk_bf16_f32 v37, v26, v27
	v_lshl_add_u64 v[26:27], s[12:13], 0, v[58:59]
	v_readlane_b32 s62, v252, 18
	v_readlane_b32 s63, v252, 19
	v_readlane_b32 s64, v252, 20
	v_readlane_b32 s65, v252, 21
	v_readlane_b32 s66, v252, 22
	v_readlane_b32 s67, v252, 23
	v_readlane_b32 s68, v252, 24
	v_readlane_b32 s69, v252, 25
	v_readlane_b32 s70, v252, 26
	v_readlane_b32 s71, v252, 27
	v_readlane_b32 s72, v252, 28
	v_readlane_b32 s73, v252, 29
	global_store_dwordx2 v[26:27], v[36:37], off
	s_and_saveexec_b64 s[24:25], s[2:3]
	s_cbranch_execz .LBB0_1064
	v_lshl_add_u64 v[26:27], v[66:67], 2, s[14:15]
	s_waitcnt lgkmcnt(0)
	v_add_f32_e32 v24, v24, v25
	global_atomic_add_f32 v[26:27], v24, off
.LBB0_1064:
	s_or_b64 exec, exec, s[24:25]
	v_add_u32_e32 v178, 0x80, v64
	v_ashrrev_i32_e32 v179, 31, v178
	v_readlane_b32 s60, v252, 16
	s_waitcnt lgkmcnt(0)
	v_lshlrev_b64 v[24:25], 13, v[178:179]
	v_readlane_b32 s74, v252, 30
	v_readlane_b32 s75, v252, 31
	v_pk_add_f32 v[46:47], v[176:177], v[46:47]
	v_pk_add_f32 v[44:45], v[174:175], v[44:45]
	v_lshl_add_u64 v[24:25], s[74:75], 0, v[24:25]
	v_lshl_add_u64 v[180:181], v[144:145], 2, v[24:25]
	global_load_dwordx4 v[64:67], v[180:181], off nt
	global_load_dwordx4 v[48:51], v[180:181], off offset:64 nt
	global_load_dwordx4 v[36:39], v[180:181], off offset:512 nt
	global_load_dwordx4 v[24:27], v[180:181], off offset:576 nt
	v_lshlrev_b64 v[56:57], 11, v[212:213]
	v_mul_f32_e32 v58, v45, v45
	v_mul_f32_e32 v59, v47, v47
	v_lshl_add_u64 v[56:57], v[56:57], 0, v[144:145]
	global_store_dwordx4 v[214:215], v[44:47], off
	v_fmac_f32_e32 v58, v44, v44
	v_fmac_f32_e32 v59, v46, v46
	v_pk_mul_f32 v[46:47], v[14:15], v[46:47]
	v_pk_mul_f32 v[44:45], v[12:13], v[44:45]
	v_pk_add_f32 v[34:35], v[172:173], v[34:35]
	v_cvt_pk_bf16_f32 v44, v44, v45
	v_cvt_pk_bf16_f32 v45, v46, v47
	v_lshlrev_b64 v[46:47], 1, v[56:57]
	v_lshl_add_u64 v[56:57], s[12:13], 0, v[46:47]
	v_pk_add_f32 v[32:33], v[170:171], v[32:33]
	global_store_dwordx2 v[56:57], v[44:45], off
	v_mul_f32_e32 v44, v33, v33
	v_mul_f32_e32 v45, v35, v35
	global_store_dwordx4 v[214:215], v[32:35], off offset:64
	v_fmac_f32_e32 v44, v32, v32
	v_fmac_f32_e32 v45, v34, v34
	v_pk_mul_f32 v[34:35], v[10:11], v[34:35]
	v_pk_mul_f32 v[32:33], v[8:9], v[32:33]
	v_pk_add_f32 v[22:23], v[168:169], v[22:23]
	v_cvt_pk_bf16_f32 v32, v32, v33
	v_cvt_pk_bf16_f32 v33, v34, v35
	v_or_b32_e32 v34, 32, v46
	v_mov_b32_e32 v35, v47
	v_lshl_add_u64 v[34:35], s[12:13], 0, v[34:35]
	v_pk_add_f32 v[20:21], v[166:167], v[20:21]
	global_store_dwordx2 v[34:35], v[32:33], off
	v_mul_f32_e32 v32, v21, v21
	v_mul_f32_e32 v33, v23, v23
	global_store_dwordx4 v[214:215], v[20:23], off offset:512
	v_fmac_f32_e32 v32, v20, v20
	v_fmac_f32_e32 v33, v22, v22
	v_pk_mul_f32 v[22:23], v[6:7], v[22:23]
	v_pk_mul_f32 v[20:21], v[4:5], v[20:21]
	v_pk_add_f32 v[18:19], v[164:165], v[18:19]
	v_cvt_pk_bf16_f32 v20, v20, v21
	v_cvt_pk_bf16_f32 v21, v22, v23
	v_or_b32_e32 v22, 0x100, v46
	v_mov_b32_e32 v23, v47
	v_lshl_add_u64 v[22:23], s[12:13], 0, v[22:23]
	v_pk_add_f32 v[16:17], v[162:163], v[16:17]
	v_add_f32_e32 v58, v58, v59
	v_add_f32_e32 v44, v44, v45
	global_store_dwordx2 v[22:23], v[20:21], off
	v_mul_f32_e32 v20, v17, v17
	v_mul_f32_e32 v21, v19, v19
	v_add_f32_e32 v44, v58, v44
	v_add_f32_e32 v32, v32, v33
	v_fmac_f32_e32 v20, v16, v16
	v_fmac_f32_e32 v21, v18, v18
	v_add_f32_e32 v32, v44, v32
	v_add_f32_e32 v20, v20, v21
	v_add_f32_e32 v21, v32, v20
	ds_bpermute_b32 v22, v227, v21
	global_store_dwordx4 v[214:215], v[16:19], off offset:576
	v_or_b32_e32 v46, 0x120, v46
	v_readlane_b32 s61, v252, 17
	v_pk_mul_f32 v[16:17], v[0:1], v[16:17]
	v_pk_mul_f32 v[18:19], v[2:3], v[18:19]
	v_cvt_pk_bf16_f32 v20, v16, v17
	s_waitcnt lgkmcnt(0)
	v_add_f32_e32 v16, v21, v22
	ds_bpermute_b32 v17, v226, v16
	v_cvt_pk_bf16_f32 v21, v18, v19
	v_lshl_add_u64 v[18:19], s[12:13], 0, v[46:47]
	v_readlane_b32 s62, v252, 18
	v_readlane_b32 s63, v252, 19
	v_readlane_b32 s64, v252, 20
	v_readlane_b32 s65, v252, 21
	v_readlane_b32 s66, v252, 22
	v_readlane_b32 s67, v252, 23
	v_readlane_b32 s68, v252, 24
	v_readlane_b32 s69, v252, 25
	v_readlane_b32 s70, v252, 26
	v_readlane_b32 s71, v252, 27
	v_readlane_b32 s72, v252, 28
	v_readlane_b32 s73, v252, 29
	global_store_dwordx2 v[18:19], v[20:21], off
	s_and_saveexec_b64 s[24:25], s[2:3]
	s_cbranch_execz .LBB0_1066
	v_lshl_add_u64 v[18:19], v[212:213], 2, s[14:15]
	s_waitcnt lgkmcnt(0)
	v_add_f32_e32 v16, v16, v17
	global_atomic_add_f32 v[18:19], v16, off
.LBB0_1066:
	s_or_b64 exec, exec, s[24:25]
	s_waitcnt lgkmcnt(0)
	v_lshl_add_u64 v[16:17], v[144:145], 2, v[210:211]
	v_lshl_add_u64 v[162:163], v[16:17], 0, s[20:21]
	v_add_co_u32_e32 v16, vcc, 0x120000, v16
	v_lshlrev_b64 v[20:21], 11, v[194:195]
	s_nop 0
	v_addc_co_u32_e32 v17, vcc, 0, v17, vcc
	global_load_dwordx4 v[44:47], v[162:163], off offset:64 nt
	global_load_dwordx4 v[32:35], v[162:163], off offset:512 nt
	global_load_dwordx4 v[56:59], v[16:17], off nt
	s_nop 0
	global_load_dwordx4 v[16:19], v[162:163], off offset:576 nt
	v_lshl_add_u64 v[164:165], v[20:21], 0, v[144:145]
	s_waitcnt vmcnt(27)
	v_pk_add_f32 v[22:23], v[160:161], v[62:63]
	v_pk_add_f32 v[20:21], v[158:159], v[60:61]
	v_mul_f32_e32 v61, v23, v23
	v_mul_f32_e32 v60, v21, v21
	v_fmac_f32_e32 v60, v20, v20
	v_fmac_f32_e32 v61, v22, v22
	global_store_dwordx4 v[196:197], v[20:23], off
	v_add_f32_e32 v62, v60, v61
	v_lshlrev_b64 v[60:61], 1, v[164:165]
	v_pk_mul_f32 v[22:23], v[14:15], v[22:23]
	v_pk_mul_f32 v[20:21], v[12:13], v[20:21]
	s_nop 0
	v_cvt_pk_bf16_f32 v20, v20, v21
	v_cvt_pk_bf16_f32 v21, v22, v23
	v_lshl_add_u64 v[22:23], s[12:13], 0, v[60:61]
	global_store_dwordx2 v[22:23], v[20:21], off
	s_waitcnt vmcnt(28)
	v_pk_add_f32 v[22:23], v[156:157], v[54:55]
	v_pk_add_f32 v[20:21], v[154:155], v[52:53]
	v_mul_f32_e32 v53, v23, v23
	v_mul_f32_e32 v52, v21, v21
	global_store_dwordx4 v[196:197], v[20:23], off offset:64
	v_fmac_f32_e32 v52, v20, v20
	v_fmac_f32_e32 v53, v22, v22
	v_pk_mul_f32 v[22:23], v[10:11], v[22:23]
	v_pk_mul_f32 v[20:21], v[8:9], v[20:21]
	v_add_f32_e32 v52, v52, v53
	v_cvt_pk_bf16_f32 v20, v20, v21
	v_cvt_pk_bf16_f32 v21, v22, v23
	v_or_b32_e32 v22, 32, v60
	v_mov_b32_e32 v23, v61
	v_lshl_add_u64 v[22:23], s[12:13], 0, v[22:23]
	global_store_dwordx2 v[22:23], v[20:21], off
	s_waitcnt vmcnt(29)
	v_pk_add_f32 v[22:23], v[152:153], v[42:43]
	v_pk_add_f32 v[20:21], v[150:151], v[40:41]
	v_mul_f32_e32 v41, v23, v23
	v_mul_f32_e32 v40, v21, v21
	global_store_dwordx4 v[196:197], v[20:23], off offset:512
	v_fmac_f32_e32 v40, v20, v20
	v_fmac_f32_e32 v41, v22, v22
	v_pk_mul_f32 v[22:23], v[6:7], v[22:23]
	v_pk_mul_f32 v[20:21], v[4:5], v[20:21]
	v_add_f32_e32 v52, v62, v52
	v_cvt_pk_bf16_f32 v20, v20, v21
	v_cvt_pk_bf16_f32 v21, v22, v23
	v_or_b32_e32 v22, 0x100, v60
	v_mov_b32_e32 v23, v61
	v_lshl_add_u64 v[22:23], s[12:13], 0, v[22:23]
	global_store_dwordx2 v[22:23], v[20:21], off
	s_waitcnt vmcnt(30)
	v_pk_add_f32 v[22:23], v[148:149], v[30:31]
	v_pk_add_f32 v[20:21], v[146:147], v[28:29]
	v_mul_f32_e32 v29, v23, v23
	v_mul_f32_e32 v28, v21, v21
	v_add_f32_e32 v40, v40, v41
	v_fmac_f32_e32 v28, v20, v20
	v_fmac_f32_e32 v29, v22, v22
	v_add_f32_e32 v40, v52, v40
	v_add_f32_e32 v28, v28, v29
	v_add_f32_e32 v29, v40, v28
	ds_bpermute_b32 v30, v227, v29
	global_store_dwordx4 v[196:197], v[20:23], off offset:576
	v_or_b32_e32 v60, 0x120, v60
	s_nop 0
	v_pk_mul_f32 v[20:21], v[0:1], v[20:21]
	v_pk_mul_f32 v[22:23], v[2:3], v[22:23]
	v_cvt_pk_bf16_f32 v28, v20, v21
	s_waitcnt lgkmcnt(0)
	v_add_f32_e32 v20, v29, v30
	ds_bpermute_b32 v21, v226, v20
	v_cvt_pk_bf16_f32 v29, v22, v23
	v_lshl_add_u64 v[22:23], s[12:13], 0, v[60:61]
	global_store_dwordx2 v[22:23], v[28:29], off
	s_and_saveexec_b64 s[24:25], s[2:3]
	s_cbranch_execz .LBB0_1068
	v_lshl_add_u64 v[22:23], v[194:195], 2, s[14:15]
	s_waitcnt lgkmcnt(0)
	v_add_f32_e32 v20, v20, v21
	global_atomic_add_f32 v[22:23], v20, off
.LBB0_1068:
	s_or_b64 exec, exec, s[24:25]
	v_or_b32_e32 v146, 32, v178
	v_ashrrev_i32_e32 v147, 31, v146
	v_readlane_b32 s60, v252, 16
	s_waitcnt lgkmcnt(0)
	v_lshlrev_b64 v[20:21], 13, v[146:147]
	v_readlane_b32 s74, v252, 30
	v_readlane_b32 s75, v252, 31
	v_lshlrev_b64 v[60:61], 11, v[178:179]
	v_lshl_add_u64 v[150:151], v[60:61], 0, v[144:145]
	v_lshl_add_u64 v[20:21], s[74:75], 0, v[20:21]
	v_lshl_add_u64 v[148:149], v[144:145], 2, v[20:21]
	global_load_dwordx4 v[52:55], v[148:149], off nt
	global_load_dwordx4 v[40:43], v[148:149], off offset:64 nt
	global_load_dwordx4 v[28:31], v[148:149], off offset:512 nt
	global_load_dwordx4 v[20:23], v[148:149], off offset:576 nt
	s_waitcnt vmcnt(27)
	v_pk_add_f32 v[62:63], v[142:143], v[66:67]
	v_pk_add_f32 v[60:61], v[140:141], v[64:65]
	v_mul_f32_e32 v65, v63, v63
	v_mul_f32_e32 v64, v61, v61
	global_store_dwordx4 v[180:181], v[60:63], off
	v_fmac_f32_e32 v64, v60, v60
	v_fmac_f32_e32 v65, v62, v62
	v_pk_mul_f32 v[62:63], v[14:15], v[62:63]
	v_pk_mul_f32 v[60:61], v[12:13], v[60:61]
	v_add_f32_e32 v66, v64, v65
	v_cvt_pk_bf16_f32 v60, v60, v61
	v_cvt_pk_bf16_f32 v61, v62, v63
	v_lshlrev_b64 v[62:63], 1, v[150:151]
	v_lshl_add_u64 v[64:65], s[12:13], 0, v[62:63]
	s_waitcnt vmcnt(27)
	v_pk_add_f32 v[50:51], v[126:127], v[50:51]
	v_pk_add_f32 v[48:49], v[124:125], v[48:49]
	global_store_dwordx2 v[64:65], v[60:61], off
	v_mul_f32_e32 v60, v49, v49
	v_mul_f32_e32 v61, v51, v51
	global_store_dwordx4 v[180:181], v[48:51], off offset:64
	v_fmac_f32_e32 v60, v48, v48
	v_fmac_f32_e32 v61, v50, v50
	v_pk_mul_f32 v[50:51], v[10:11], v[50:51]
	v_pk_mul_f32 v[48:49], v[8:9], v[48:49]
	s_waitcnt vmcnt(28)
	v_pk_add_f32 v[38:39], v[122:123], v[38:39]
	v_cvt_pk_bf16_f32 v48, v48, v49
	v_cvt_pk_bf16_f32 v49, v50, v51
	v_or_b32_e32 v50, 32, v62
	v_mov_b32_e32 v51, v63
	v_lshl_add_u64 v[50:51], s[12:13], 0, v[50:51]
	v_pk_add_f32 v[36:37], v[120:121], v[36:37]
	global_store_dwordx2 v[50:51], v[48:49], off
	v_mul_f32_e32 v48, v37, v37
	v_mul_f32_e32 v49, v39, v39
	global_store_dwordx4 v[180:181], v[36:39], off offset:512
	v_fmac_f32_e32 v48, v36, v36
	v_fmac_f32_e32 v49, v38, v38
	v_pk_mul_f32 v[38:39], v[6:7], v[38:39]
	v_pk_mul_f32 v[36:37], v[4:5], v[36:37]
	s_waitcnt vmcnt(29)
	v_pk_add_f32 v[26:27], v[118:119], v[26:27]
	v_cvt_pk_bf16_f32 v36, v36, v37
	v_cvt_pk_bf16_f32 v37, v38, v39
	v_or_b32_e32 v38, 0x100, v62
	v_mov_b32_e32 v39, v63
	v_lshl_add_u64 v[38:39], s[12:13], 0, v[38:39]
	v_pk_add_f32 v[24:25], v[116:117], v[24:25]
	v_add_f32_e32 v60, v60, v61
	global_store_dwordx2 v[38:39], v[36:37], off
	v_mul_f32_e32 v36, v25, v25
	v_mul_f32_e32 v37, v27, v27
	v_add_f32_e32 v60, v66, v60
	v_add_f32_e32 v48, v48, v49
	v_fmac_f32_e32 v36, v24, v24
	v_fmac_f32_e32 v37, v26, v26
	v_add_f32_e32 v48, v60, v48
	v_add_f32_e32 v36, v36, v37
	v_add_f32_e32 v37, v48, v36
	ds_bpermute_b32 v38, v227, v37
	global_store_dwordx4 v[180:181], v[24:27], off offset:576
	v_or_b32_e32 v62, 0x120, v62
	v_readlane_b32 s61, v252, 17
	v_pk_mul_f32 v[24:25], v[0:1], v[24:25]
	v_pk_mul_f32 v[26:27], v[2:3], v[26:27]
	v_cvt_pk_bf16_f32 v36, v24, v25
	s_waitcnt lgkmcnt(0)
	v_add_f32_e32 v24, v37, v38
	ds_bpermute_b32 v25, v226, v24
	v_cvt_pk_bf16_f32 v37, v26, v27
	v_lshl_add_u64 v[26:27], s[12:13], 0, v[62:63]
	v_readlane_b32 s62, v252, 18
	v_readlane_b32 s63, v252, 19
	v_readlane_b32 s64, v252, 20
	v_readlane_b32 s65, v252, 21
	v_readlane_b32 s66, v252, 22
	v_readlane_b32 s67, v252, 23
	v_readlane_b32 s68, v252, 24
	v_readlane_b32 s69, v252, 25
	v_readlane_b32 s70, v252, 26
	v_readlane_b32 s71, v252, 27
	v_readlane_b32 s72, v252, 28
	v_readlane_b32 s73, v252, 29
	global_store_dwordx2 v[26:27], v[36:37], off
	s_and_saveexec_b64 s[24:25], s[2:3]
	s_cbranch_execz .LBB0_1070
	v_lshl_add_u64 v[26:27], v[178:179], 2, s[14:15]
	s_waitcnt lgkmcnt(0)
	v_add_f32_e32 v24, v24, v25
	global_atomic_add_f32 v[26:27], v24, off
.LBB0_1070:
	s_or_b64 exec, exec, s[24:25]
	v_or_b32_e32 v64, 48, v178
	v_ashrrev_i32_e32 v65, 31, v64
	v_readlane_b32 s60, v252, 16
	s_waitcnt lgkmcnt(0)
	v_lshlrev_b64 v[24:25], 13, v[64:65]
	v_readlane_b32 s74, v252, 30
	v_readlane_b32 s75, v252, 31
	v_or_b32_e32 v116, 16, v178
	v_ashrrev_i32_e32 v117, 31, v116
	v_lshl_add_u64 v[24:25], s[74:75], 0, v[24:25]
	v_lshl_add_u64 v[66:67], v[144:145], 2, v[24:25]
	global_load_dwordx4 v[60:63], v[66:67], off nt
	global_load_dwordx4 v[48:51], v[66:67], off offset:64 nt
	global_load_dwordx4 v[36:39], v[66:67], off offset:512 nt
	global_load_dwordx4 v[24:27], v[66:67], off offset:576 nt
	s_waitcnt vmcnt(25)
	v_pk_add_f32 v[58:59], v[114:115], v[58:59]
	v_pk_add_f32 v[56:57], v[112:113], v[56:57]
	v_lshlrev_b64 v[118:119], 11, v[116:117]
	v_mul_f32_e32 v112, v57, v57
	v_mul_f32_e32 v113, v59, v59
	v_lshl_add_u64 v[118:119], v[118:119], 0, v[144:145]
	global_store_dwordx4 v[162:163], v[56:59], off
	v_fmac_f32_e32 v112, v56, v56
	v_fmac_f32_e32 v113, v58, v58
	v_pk_mul_f32 v[58:59], v[14:15], v[58:59]
	v_pk_mul_f32 v[56:57], v[12:13], v[56:57]
	v_add_f32_e32 v114, v112, v113
	v_cvt_pk_bf16_f32 v56, v56, v57
	v_cvt_pk_bf16_f32 v57, v58, v59
	v_lshlrev_b64 v[58:59], 1, v[118:119]
	v_lshl_add_u64 v[112:113], s[12:13], 0, v[58:59]
	v_pk_add_f32 v[46:47], v[110:111], v[46:47]
	v_pk_add_f32 v[44:45], v[108:109], v[44:45]
	global_store_dwordx2 v[112:113], v[56:57], off
	v_mul_f32_e32 v56, v45, v45
	v_mul_f32_e32 v57, v47, v47
	global_store_dwordx4 v[162:163], v[44:47], off offset:64
	v_fmac_f32_e32 v56, v44, v44
	v_fmac_f32_e32 v57, v46, v46
	v_pk_mul_f32 v[46:47], v[10:11], v[46:47]
	v_pk_mul_f32 v[44:45], v[8:9], v[44:45]
	v_pk_add_f32 v[34:35], v[106:107], v[34:35]
	v_cvt_pk_bf16_f32 v44, v44, v45
	v_cvt_pk_bf16_f32 v45, v46, v47
	v_or_b32_e32 v46, 32, v58
	v_mov_b32_e32 v47, v59
	v_lshl_add_u64 v[46:47], s[12:13], 0, v[46:47]
	v_pk_add_f32 v[32:33], v[104:105], v[32:33]
	global_store_dwordx2 v[46:47], v[44:45], off
	v_mul_f32_e32 v44, v33, v33
	v_mul_f32_e32 v45, v35, v35
	global_store_dwordx4 v[162:163], v[32:35], off offset:512
	v_fmac_f32_e32 v44, v32, v32
	v_fmac_f32_e32 v45, v34, v34
	v_pk_mul_f32 v[34:35], v[6:7], v[34:35]
	v_pk_mul_f32 v[32:33], v[4:5], v[32:33]
	s_waitcnt vmcnt(29)
	v_pk_add_f32 v[18:19], v[102:103], v[18:19]
	v_cvt_pk_bf16_f32 v32, v32, v33
	v_cvt_pk_bf16_f32 v33, v34, v35
	v_or_b32_e32 v34, 0x100, v58
	v_mov_b32_e32 v35, v59
	v_lshl_add_u64 v[34:35], s[12:13], 0, v[34:35]
	v_pk_add_f32 v[16:17], v[100:101], v[16:17]
	v_add_f32_e32 v56, v56, v57
	global_store_dwordx2 v[34:35], v[32:33], off
	v_mul_f32_e32 v32, v17, v17
	v_mul_f32_e32 v33, v19, v19
	v_add_f32_e32 v56, v114, v56
	v_add_f32_e32 v44, v44, v45
	v_fmac_f32_e32 v32, v16, v16
	v_fmac_f32_e32 v33, v18, v18
	v_add_f32_e32 v44, v56, v44
	v_add_f32_e32 v32, v32, v33
	v_add_f32_e32 v33, v44, v32
	ds_bpermute_b32 v34, v227, v33
	global_store_dwordx4 v[162:163], v[16:19], off offset:576
	v_or_b32_e32 v58, 0x120, v58
	v_readlane_b32 s61, v252, 17
	v_pk_mul_f32 v[16:17], v[0:1], v[16:17]
	v_pk_mul_f32 v[18:19], v[2:3], v[18:19]
	v_cvt_pk_bf16_f32 v32, v16, v17
	s_waitcnt lgkmcnt(0)
	v_add_f32_e32 v16, v33, v34
	ds_bpermute_b32 v17, v226, v16
	v_cvt_pk_bf16_f32 v33, v18, v19
	v_lshl_add_u64 v[18:19], s[12:13], 0, v[58:59]
	v_readlane_b32 s62, v252, 18
	v_readlane_b32 s63, v252, 19
	v_readlane_b32 s64, v252, 20
	v_readlane_b32 s65, v252, 21
	v_readlane_b32 s66, v252, 22
	v_readlane_b32 s67, v252, 23
	v_readlane_b32 s68, v252, 24
	v_readlane_b32 s69, v252, 25
	v_readlane_b32 s70, v252, 26
	v_readlane_b32 s71, v252, 27
	v_readlane_b32 s72, v252, 28
	v_readlane_b32 s73, v252, 29
	global_store_dwordx2 v[18:19], v[32:33], off
	s_and_saveexec_b64 s[24:25], s[2:3]
	s_cbranch_execz .LBB0_1072
	v_lshl_add_u64 v[18:19], v[116:117], 2, s[14:15]
	s_waitcnt lgkmcnt(0)
	v_add_f32_e32 v16, v16, v17
	global_atomic_add_f32 v[18:19], v16, off
